# SSD: C tile fragments loaded straight to registers (no LDS), plain head-dim fragment layout for output path (2-way instead of 4-way LDS conflicts, 8-byte y stores)
# speedup vs baseline: 1.0285x; 1.0097x over previous
; #define LAS __attribute__((address_space(3)))
; __device__ __forceinline__ void phase_C1(const Args& a, unsigned char* ws, const int bid, int l, LAS unsigned char* lds, int tid, int wave, int lane) {
;     bf16_t* z = (bf16_t*)(ws + WS_Z);
;     const bf16_t* xbc = (const bf16_t*)(ws + WS_XBC);
;     const float* DT = (const float*)(ws + WS_DT);
;     LAS unsigned char* L_C = lds; LAS unsigned char* L_B = lds + 34816; LAS unsigned char* L_M = lds + 69632; LAS unsigned char* L_X = lds + 104448; LAS unsigned char* L_H = lds + 122880;
;     LAS float* cs = (LAS float*)(lds + 140288); LAS float* dtv = cs + 128; LAS float* wgt = cs + 256; LAS float* ecs = cs + 384; LAS float* f2dt = cs + 512; LAS float* refarr = cs + 640; LAS float* totp = cs + 656;
;     const int fr = lane & 15, fq = lane >> 4, wr = wave >> 1, wc = wave & 1;
;     const int qt = wave < 4 ? wave : 11 - wave;
;     const int rb = fr * 272 + fq * 16;
;     const int trB = (8 * fq + (fr >> 2)) * 272 + 8 * (lane & 3);
;     const int trX = (8 * fq + (fr >> 2)) * 144 + 8 * (lane & 3);
;     const int trXp = (8 * fq + (fr >> 2)) * 144 + 16 * (lane & 3);
;     const int rbH = (8 * (fr >> 2) + (fr & 3)) * 272 + fq * 16;
;     const unsigned offCB = (unsigned)(tid >> 4) * 4096u + (unsigned)(tid & 15) * 8u, offX = (unsigned)(tid >> 3) * 4096u + (unsigned)(tid & 7) * 8u;
;     const int wCB = (tid >> 4) * 272 + (tid & 15) * 16, wX = (tid >> 3) * 144 + (tid & 7) * 16;
.LBB0_84:
	s_cmp_eq_u32 s60, 3
	s_mov_b64 s[0:1], -1
	s_cbranch_scc0 .LBB0_127
	v_writelane_b32 v254, s61, 54
	v_writelane_b32 v254, s62, 55
	s_cmpk_gt_i32 s68, 0xff
	s_mov_b32 s3, s33
	v_writelane_b32 v254, s63, 56
	v_writelane_b32 v254, s60, 57
	v_writelane_b32 v254, s82, 58
	s_nop 1
	v_writelane_b32 v254, s83, 59
	s_nop 0
	v_readlane_b32 s60, v254, 39
	v_readlane_b32 s61, v254, 40
	s_cbranch_scc1 .LBB0_128
	v_readlane_b32 s0, v254, 47
	v_readlane_b32 s1, v254, 48
	s_add_u32 s2, s0, 0x19afe000
	v_writelane_b32 v254, s2, 60
	s_addc_u32 s2, s1, 0
	s_add_u32 s68, s0, 0x4c37e000
	s_addc_u32 s93, s1, 0
	s_add_u32 s0, s0, 0x2be000
	v_writelane_b32 v254, s2, 61
	s_addc_u32 s1, s1, 0
	v_writelane_b32 v254, s0, 62
	v_and_b32_e32 v0, 7, v164
	v_ashrrev_i32_e32 v2, 3, v164
	v_writelane_b32 v254, s1, 63
	s_movk_i32 s2, 0x90
	v_readlane_b32 s5, v254, 49
	s_sub_i32 s0, 11, s5
	s_cmp_lt_i32 s5, 4
	v_readlane_b32 s6, v254, 58
	s_cselect_b32 s0, s5, s0
	s_lshl_b32 s3, s6, 6
	v_and_b32_e32 v6, 15, v164
	v_lshlrev_b32_e32 v7, 3, v0
	v_readlane_b32 s8, v254, 54
	v_writelane_b32 v255, s3, 0
	s_lshl_b32 s3, s6, 5
	v_mul_lo_u32 v3, v2, s2
	v_ashrrev_i32_e32 v4, 4, v164
	s_movk_i32 s10, 0x110
	v_lshl_or_b32 v104, v2, 12, v7
	v_lshlrev_b32_e32 v2, 3, v6
	s_ashr_i32 s1, s8, 7
	v_readlane_b32 s7, v254, 59
	v_writelane_b32 v255, s3, 1
	s_movk_i32 s3, 0x1100
	v_mul_lo_u32 v5, v4, s10
	v_lshl_or_b32 v106, v4, 12, v2
	v_bfe_u32 v2, v164, 2, 2
	v_and_b32_e32 v4, 3, v164
	v_lshrrev_b32_e32 v10, 4, v206
	v_cmp_gt_i32_e64 s[6:7], s3, v164
	s_cmp_lt_u32 s8, 64
	v_lshlrev_b32_e32 v15, 3, v206
	v_readlane_b32 s12, v253, 45
	v_readlane_b32 s13, v253, 46
	v_readlane_b32 s4, v253, 47
	v_readlane_b32 s14, v253, 48
	v_readlane_b32 s38, v253, 49
	v_readlane_b32 s42, v253, 50
	v_lshl_or_b32 v7, v2, 3, v4
	v_lshlrev_b32_e32 v108, 3, v10
	v_writelane_b32 v255, s6, 2
	s_cselect_b64 s[24:25], -1, 0
	s_cmp_gt_u32 s8, 63
	v_readlane_b32 s3, v253, 43
	v_add_u32_e32 v120, s12, v15
	v_add_u32_e32 v121, s13, v15
	v_add_u32_e32 v122, s4, v15
	v_add_u32_e32 v123, s14, v15
	v_add_u32_e32 v124, s38, v15
	v_mov_b32_e32 v15, s42
	v_or_b32_e32 v2, v108, v2
	v_writelane_b32 v255, s7, 3
	s_cselect_b64 s[6:7], -1, 0
	v_mad_u32_u24 v7, v7, s10, v15
	v_mov_b32_e32 v15, s3
	v_lshl_add_u32 v125, v10, 5, s4
	s_lshl_b32 s4, s5, 7
	s_lshl_b32 s5, s0, 4
	v_lshlrev_b32_e32 v9, 4, v4
	v_lshlrev_b32_e32 v4, 3, v4
	v_mul_u32_u24_e32 v11, 0x110, v2
	v_mad_u32_u24 v2, v2, s2, v15
	v_or_b32_e32 v126, s5, v6
	v_and_b32_e32 v8, 48, v164
	v_add_u32_e32 v15, v2, v4
	v_add3_u32 v4, 0, v11, v4
	v_lshlrev_b32_e32 v11, 2, v126
	v_add_u32_e32 v3, s3, v3
	v_readlane_b32 s11, v253, 44
	v_add_u32_e32 v13, s3, v8
	s_lshl_b32 s3, s1, 5
	s_and_b32 s4, s4, 0x80
	v_add_u32_e32 v127, s12, v11
	v_add_u32_e32 v128, s14, v11
	v_lshlrev_b32_e32 v10, 2, v10
	v_mul_lo_u32 v11, v126, s10
	v_mad_u32_u24 v12, v6, s10, v8
	v_add_u32_e32 v129, s11, v11
	v_or_b32_e32 v11, s5, v10
	v_lshl_or_b32 v18, s1, 4, v6
	s_cmp_eq_u32 s0, 1
	v_add_u32_e32 v118, 0, v12
	v_add_u32_e32 v12, s11, v12
	v_lshlrev_b32_e32 v16, 2, v11
	v_mul_lo_u32 v18, v18, s10
	s_cselect_b64 s[10:11], -1, 0
	s_cmp_eq_u32 s0, 2
	v_add_u32_e32 v130, s12, v16
	v_add_u32_e32 v131, s13, v16
	s_cselect_b64 s[12:13], -1, 0
	s_cmp_eq_u32 s0, 3
	s_cselect_b64 s[14:15], -1, 0
	s_cmp_eq_u32 s0, 4
	s_cselect_b64 s[16:17], -1, 0
	s_cmp_eq_u32 s0, 5
	s_cselect_b64 s[18:19], -1, 0
	s_cmp_eq_u32 s0, 6
	s_cselect_b64 s[20:21], -1, 0
	s_cmp_eq_u32 s0, 7
	v_writelane_b32 v255, s6, 4
	s_cselect_b64 s[22:23], -1, 0
	s_cmp_gt_i32 s0, 0
	v_writelane_b32 v255, s7, 5
	s_cselect_b64 s[44:45], -1, 0
	v_writelane_b32 v255, s44, 6
	s_cmp_lt_i32 s0, 0
	s_mul_i32 s33, s0, 0x1100
	v_writelane_b32 v255, s45, 7
	s_cselect_b64 s[44:45], -1, 0
	v_writelane_b32 v255, s44, 8
	s_cmp_gt_i32 s0, 1
	v_or_b32_e32 v26, 1, v11
	v_writelane_b32 v255, s45, 9
	s_cselect_b64 s[44:45], -1, 0
	v_writelane_b32 v255, s44, 10
	s_cmp_lt_i32 s0, 1
	v_lshl_add_u32 v5, v6, 4, v5
	v_writelane_b32 v255, s45, 11
	s_cselect_b64 s[44:45], -1, 0
	v_writelane_b32 v255, s44, 12
	s_cmp_gt_i32 s0, 2
	v_and_b32_e32 v19, 48, v206
	v_writelane_b32 v255, s45, 13
; __device__ __forceinline__ void phase_C1(const Args& a, unsigned char* ws, const int bid, int l, LAS unsigned char* lds, int tid, int wave, int lane) {
;     ...
;     const int fr = lane & 15, fq = lane >> 4, wr = wave >> 1, wc = wave & 1;
;     const int qt = wave < 4 ? wave : 11 - wave;
;     const int rb = fr * 272 + fq * 16;
;     const int trB = (8 * fq + (fr >> 2)) * 272 + 8 * (lane & 3);
;     const int trX = (8 * fq + (fr >> 2)) * 144 + 8 * (lane & 3);
;     const int trXp = (8 * fq + (fr >> 2)) * 144 + 16 * (lane & 3);
;     const int rbH = (8 * (fr >> 2) + (fr & 3)) * 272 + fq * 16;
;     const unsigned offCB = (unsigned)(tid >> 4) * 4096u + (unsigned)(tid & 15) * 8u, offX = (unsigned)(tid >> 3) * 4096u + (unsigned)(tid & 7) * 8u;
;     const int wCB = (tid >> 4) * 272 + (tid & 15) * 16, wX = (tid >> 3) * 144 + (tid & 7) * 16;
	s_cselect_b64 s[44:45], -1, 0
	v_writelane_b32 v255, s44, 14
	s_cmp_lt_i32 s0, 2
	v_add_u32_e32 v132, s38, v19
	v_writelane_b32 v255, s45, 15
	s_cselect_b64 s[44:45], -1, 0
	v_writelane_b32 v255, s44, 16
	s_cmp_gt_i32 s0, 3
	v_or_b32_e32 v19, 16, v10
	v_writelane_b32 v255, s45, 17
	s_cselect_b64 s[44:45], -1, 0
	v_writelane_b32 v255, s44, 18
	s_cmp_lt_i32 s0, 3
	v_or_b32_e32 v20, 32, v10
	v_writelane_b32 v255, s45, 19
	s_cselect_b64 s[44:45], -1, 0
	v_writelane_b32 v255, s44, 20
	s_cmp_gt_i32 s0, 4
	v_or_b32_e32 v21, 48, v10
	v_writelane_b32 v255, s45, 21
	s_cselect_b64 s[44:45], -1, 0
	v_writelane_b32 v255, s44, 22
	s_cmp_lt_i32 s0, 4
	v_or_b32_e32 v22, 64, v10
	v_writelane_b32 v255, s45, 23
	s_cselect_b64 s[44:45], -1, 0
	v_writelane_b32 v255, s44, 24
	s_cmp_gt_i32 s0, 5
	v_or_b32_e32 v23, 0x50, v10
	v_writelane_b32 v255, s45, 25
	s_cselect_b64 s[44:45], -1, 0
	v_writelane_b32 v255, s44, 26
	s_cmp_lt_i32 s0, 5
	v_or_b32_e32 v24, 0x60, v10
	v_writelane_b32 v255, s45, 27
	s_cselect_b64 s[44:45], -1, 0
	v_writelane_b32 v255, s44, 28
	s_cmp_gt_i32 s0, 6
	v_or_b32_e32 v25, 0x70, v10
	v_writelane_b32 v255, s45, 29
	s_cselect_b64 s[44:45], -1, 0
	v_writelane_b32 v255, s44, 30
	s_cmp_lt_i32 s0, 6
	v_add_u32_e32 v141, s4, v4
	v_writelane_b32 v255, s45, 31
	s_cselect_b64 s[44:45], -1, 0
	v_writelane_b32 v255, s44, 32
	s_cmp_gt_i32 s0, 7
	v_or_b32_e32 v4, 3, v11
	v_writelane_b32 v255, s45, 33
	s_cselect_b64 s[44:45], -1, 0
	v_writelane_b32 v255, s44, 34
	s_cmp_lt_i32 s0, 7
	s_cselect_b64 s[0:1], -1, 0
	v_writelane_b32 v255, s45, 35
	v_writelane_b32 v255, s0, 36
	v_mul_lo_u32 v17, v126, s2
	v_add_u32_e32 v140, s3, v15
	v_writelane_b32 v255, s1, 37
	v_cmp_le_u32_e64 s[0:1], v10, v6
	v_cmp_le_i32_e64 s[2:3], v4, v126
	v_lshlrev_b32_e32 v1, 4, v0
	v_writelane_b32 v255, s0, 38
	v_cmp_eq_u32_e64 s[6:7], 0, v0
	v_lshrrev_b32_e32 v0, 1, v206
	v_writelane_b32 v255, s1, 39
	v_cmp_ge_u32_e64 s[0:1], v10, v6
	v_and_b32_e32 v14, 56, v164
	v_add_u32_e32 v0, 0, v0
	v_writelane_b32 v255, s0, 40
	v_lshlrev_b32_e32 v16, 1, v11
	v_lshl_add_u32 v133, v19, 2, s38
	v_writelane_b32 v255, s1, 41
	v_cmp_lt_u32_e64 s[0:1], v10, v6
	v_or_b32_e32 v6, 2, v11
	v_lshlrev_b32_e32 v19, 1, v19
	v_writelane_b32 v255, s0, 42
	v_lshl_add_u32 v134, v20, 2, s38
	v_lshlrev_b32_e32 v20, 1, v20
	v_writelane_b32 v255, s1, 43
	v_cmp_ge_i32_e64 s[0:1], v26, v126
	v_lshl_add_u32 v135, v21, 2, s38
	v_lshlrev_b32_e32 v21, 1, v21
	v_writelane_b32 v255, s0, 44
	v_lshl_add_u32 v136, v22, 2, s38
	v_lshlrev_b32_e32 v22, 1, v22
	v_writelane_b32 v255, s1, 45
	s_add_i32 s0, s4, s42
	v_add_u32_e32 v10, s0, v18
	v_cmp_le_i32_e64 s[0:1], v6, v126
	v_lshl_add_u32 v137, v23, 2, s38
	v_lshlrev_b32_e32 v23, 1, v23
	v_writelane_b32 v255, s0, 46
	v_lshl_add_u32 v138, v24, 2, s38
	v_lshlrev_b32_e32 v24, 1, v24
	v_writelane_b32 v255, s1, 47
	v_cmp_ge_i32_e64 s[0:1], v6, v126
	v_lshl_add_u32 v139, v25, 2, s38
	v_lshlrev_b32_e32 v25, 1, v25
	v_writelane_b32 v255, s0, 48
	v_add_u32_e32 v146, 0x22e00, v0
	v_and_or_b32 v0, v201, 64, v14
	v_writelane_b32 v255, s1, 49
	v_writelane_b32 v255, s2, 50
	v_readlane_b32 s0, v254, 53
	v_mov_b32_e32 v107, v161
	v_writelane_b32 v255, s3, 51
	v_cmp_ge_i32_e64 s[2:3], v4, v126
	v_mov_b32_e32 v105, v161
	v_lshlrev_b32_e32 v109, 1, v206
	v_writelane_b32 v255, s2, 52
	v_or_b32_e32 v119, 7, v206
	v_cmp_eq_u32_e64 s[8:9], 0, v206
	v_add_u32_e32 v142, 0xfffffe00, v164
	v_lshl_add_u32 v143, v164, 2, s42
	v_lshlrev_b32_e32 v160, 1, v108
	v_add_u32_e32 v144, 0, v5
	v_add_u32_e32 v145, v3, v1
	v_add_u32_e32 v147, v7, v8
	v_add_u32_e32 v148, v129, v19
	v_add_u32_e32 v149, v129, v20
	s_waitcnt lgkmcnt(0)
	v_add_u32_e32 v150, v129, v21
	v_add_u32_e32 v151, v129, v22
	v_add_u32_e32 v152, v129, v23
	v_add_u32_e32 v153, v129, v24
	v_add_u32_e32 v154, v129, v25
	v_add_u32_e32 v155, v129, v16
	v_add_u32_e32 v156, s33, v12
	v_add_u32_e32 v157, v2, v9
	v_add_u32_e32 v158, v10, v108
	v_lshlrev_b32_e32 v159, 2, v0
	v_add_u32_e32 v165, v13, v17
	v_add_u32_e32 v147, 0x1e000, v118
	v_and_b32_e32 v0, 3, v164
	v_lshlrev_b32_e32 v0, 3, v0
	v_sub_u32_e32 v157, v157, v0
	s_mov_b32 s1, s0
	v_writelane_b32 v255, s3, 53
	s_branch .LBB0_88

; __device__ __forceinline__ void phase_C1(const Args& a, unsigned char* ws, const int bid, int l, LAS unsigned char* lds, int tid, int wave, int lane) {
;     ...
;         SSD_ISSUE(0);
.LBB0_91:
	s_or_b64 exec, exec, s[0:1]
	s_ashr_i32 s46, s5, 4
	s_lshl_b32 s0, s46, 8
	s_lshl_b32 s1, s4, 7
	s_or_b32 s0, s0, s1
	s_ashr_i32 s1, s0, 31
	s_lshl_b64 s[42:43], s[0:1], 13
	s_add_u32 s1, s68, s42
	s_addc_u32 s5, s93, s43
	s_lshl_b32 s38, s3, 8
	s_add_u32 s42, s1, s38
	s_addc_u32 s43, s5, 0
	s_mov_b64 s[90:91], s[42:43]
	s_waitcnt vmcnt(7)
	v_lshl_add_u64 v[24:25], v[106:107], 1, s[42:43]
	v_add_co_u32_e32 v4, vcc, s70, v24
	s_mov_b32 s84, 0x41000
	s_nop 0
	v_addc_co_u32_e32 v5, vcc, 0, v25, vcc
	v_add_co_u32_e32 v12, vcc, s84, v24
	s_mov_b32 s85, 0x81000
	s_nop 0
	v_addc_co_u32_e32 v13, vcc, 0, v25, vcc
	s_mov_b64 s[42:43], 0x1000
	v_add_co_u32_e32 v20, vcc, s85, v24
	s_lshl_b32 s38, s44, 7
	v_lshl_add_u64 v[0:1], v[24:25], 0, s[42:43]
	v_addc_co_u32_e32 v21, vcc, 0, v25, vcc
	s_mov_b32 s86, 0xc1000
	s_add_u32 s42, s1, s38
	s_waitcnt vmcnt(6)
	v_add_co_u32_e32 v28, vcc, s86, v24
	s_addc_u32 s43, s5, 0
	s_nop 0
	v_addc_co_u32_e32 v29, vcc, 0, v25, vcc
	s_waitcnt vmcnt(5)
	v_lshl_add_u64 v[32:33], v[104:105], 1, s[42:43]
	s_waitcnt vmcnt(4)
	v_add_co_u32_e32 v36, vcc, 0x80000, v32
	global_load_dwordx4 v[0:3], v[0:1], off offset:2048
	s_nop 0
	global_load_dwordx4 v[4:7], v[4:5], off
	v_addc_co_u32_e32 v37, vcc, 0, v33, vcc
	global_load_dwordx4 v[8:11], v[12:13], off offset:2048
	s_nop 0
	global_load_dwordx4 v[12:15], v[12:13], off
	s_nop 0
	global_load_dwordx4 v[16:19], v[20:21], off offset:2048
	s_nop 0
	global_load_dwordx4 v[20:23], v[20:21], off
	s_nop 0
	global_load_dwordx4 v[24:27], v[28:29], off offset:2048
	s_nop 0
	global_load_dwordx4 v[28:31], v[28:29], off
	s_nop 0
	global_load_dwordx4 v[32:35], v[32:33], off nt
	s_nop 0
	global_load_dwordx4 v[36:39], v[36:37], off nt
	v_readlane_b32 s42, v255, 4
	v_readlane_b32 s43, v255, 5
	s_movk_i32 s2, 0x6200
	s_andn2_b64 vcc, exec, s[42:43]
	s_mov_b64 s[42:43], -1
	s_cbranch_vccnz .LBB0_93
	s_mov_b64 s[42:43], 0

; #define LAS __attribute__((address_space(3)))
; __device__ __forceinline__ unsigned cvt_pk_bf16(float lo, float hi) { unsigned r; asm volatile("v_cvt_pk_bf16_f32 %0, %1, %2" : "=v"(r) : "v"(lo), "v"(hi)); return r; }
; #define INP(k) inp_(a.in[k])
; #define LDS_BARRIER() do { asm volatile("s_waitcnt lgkmcnt(0)" ::: "memory"); __builtin_amdgcn_s_barrier(); asm volatile("" ::: "memory"); } while (0)
; __device__ __forceinline__ void phase_C1(const Args& a, unsigned char* ws, const int bid, int l, LAS unsigned char* lds, int tid, int wave, int lane) {
;     ...
;         const int combo = (item & 7) * 8 + (item >> 5), hq = (item >> 3) & 3;
;         const int b = combo >> 4, g = (combo >> 1) & 7, dir = combo & 1, h = 4 * g + hq;
;         const float Acoef = -__expf(INP(12)[l * 64 + dir * 32 + h]);
;         const float dskip = INP(13)[l * 32 + h];
;         f32x4 Hacc[4];
; #pragma unroll
;         for (int j = 0; j < 4; ++j) Hacc[j] = (f32x4){0.f, 0.f, 0.f, 0.f};
;         for (int i = tid; i < 17408 / 4; i += 512) ((LAS unsigned*)L_H)[i] = 0u;
;         u32x4 pc[4], pb[4], px[2]; float pd0 = 0.f, pd1 = 0.f;
;     ...
;         SSD_ISSUE(0);
; #pragma unroll 1
;         for (int step = 0; step < 66; ++step) {
;             const int row0 = SSD_GC(step) * 128;
; #pragma unroll
;             for (int i = 0; i < 4; ++i) { *(LAS u32x4*)(L_C + wCB + i * 32 * 272) = pc[i]; *(LAS u32x4*)(L_B + wCB + i * 32 * 272) = pb[i]; }
;     ...
;             LDS_BARRIER();
; #pragma unroll
;             for (int j = 0; j < 4; ++j) { u32x2 o; o.x = cvt_pk_bf16(Hacc[j][0], Hacc[j][1]); o.y = cvt_pk_bf16(Hacc[j][2], Hacc[j][3]);
;                 *(LAS u32x2*)(L_H + (wr * 16 + fr) * 272 + ((4 * wc + j) * 16 + fq * 4) * 2) = o; }
.LBB0_95:
	s_cmp_lg_u32 s4, 0
	s_cselect_b64 s[70:71], -1, 0
	s_lshl_b32 s5, s46, 6
	s_add_i32 s0, s5, 0x49
	v_writelane_b32 v255, s0, 55
	s_lshl_b32 s94, s46, 1
	s_or_b32 s0, s5, 6
	s_or_b32 s3, s94, 1
	v_writelane_b32 v255, s0, 56
	s_lshl_b32 s0, s45, 2
	v_readlane_b32 s42, v254, 62
	v_readlane_b32 s43, v254, 63
	s_add_u32 s0, s42, s0
	s_addc_u32 s38, s43, 0
	s_lshl_b32 s42, s44, 2
	s_add_u32 s88, s0, s42
	s_addc_u32 s89, s38, 0
	s_lshl_b32 s0, s4, 12
	v_readlane_b32 s38, v254, 60
	s_add_u32 s0, s38, s0
	v_readlane_b32 s38, v254, 61
	s_addc_u32 s43, s38, 0
	s_lshl_b32 s38, s47, 1
	s_add_u32 s42, s0, s38
	s_addc_u32 s43, s43, 0
	v_lshl_add_u64 v[114:115], s[42:43], 0, v[160:161]
	v_readlane_b32 s42, v255, 8
	s_waitcnt vmcnt(11)
	v_mul_f32_e32 v41, 0x3fb8aa3b, v41
	v_readlane_b32 s43, v255, 9
	v_exp_f32_e32 v166, v41
	s_cmp_eq_u32 s4, 0
	v_cndmask_b32_e64 v41, 0, 1, s[42:43]
	v_readlane_b32 s42, v255, 6
	v_readlane_b32 s43, v255, 7
	v_readlane_b32 s44, v255, 12
	v_readlane_b32 s45, v255, 13
	v_cndmask_b32_e64 v42, 0, 1, s[42:43]
	s_cselect_b64 s[42:43], -1, 0
	v_cndmask_b32_e64 v41, v41, v42, s[42:43]
	v_cndmask_b32_e64 v42, 0, 1, s[44:45]
	v_readlane_b32 s44, v255, 10
	v_readlane_b32 s45, v255, 11
	v_and_b32_e32 v41, 1, v41
	v_readlane_b32 s60, v255, 38
	v_cndmask_b32_e64 v43, 0, 1, s[44:45]
	v_readlane_b32 s44, v255, 16
	v_readlane_b32 s45, v255, 17
	v_cndmask_b32_e64 v42, v42, v43, s[42:43]
	v_readlane_b32 s61, v255, 39
	v_cndmask_b32_e64 v43, 0, 1, s[44:45]
	v_readlane_b32 s44, v255, 14
	v_readlane_b32 s45, v255, 15
	v_readlane_b32 s62, v255, 42
	v_readlane_b32 s63, v255, 43
	v_cndmask_b32_e64 v44, 0, 1, s[44:45]
	v_readlane_b32 s44, v255, 20
	v_readlane_b32 s45, v255, 21
	v_cndmask_b32_e64 v43, v43, v44, s[42:43]
	v_readlane_b32 s64, v255, 46
	v_cndmask_b32_e64 v44, 0, 1, s[44:45]
	v_readlane_b32 s44, v255, 18
	v_readlane_b32 s45, v255, 19
	v_readlane_b32 s65, v255, 47
	v_readlane_b32 s66, v255, 50
	v_cndmask_b32_e64 v45, 0, 1, s[44:45]
	v_readlane_b32 s44, v255, 24
	v_readlane_b32 s45, v255, 25
	v_cndmask_b32_e64 v44, v44, v45, s[42:43]
	v_readlane_b32 s67, v255, 51
	v_cndmask_b32_e64 v45, 0, 1, s[44:45]
	v_readlane_b32 s44, v255, 22
	v_readlane_b32 s45, v255, 23
	s_mov_b32 s74, 0
	s_waitcnt vmcnt(10)
	v_mov_b32_e32 v111, v110
	v_cndmask_b32_e64 v46, 0, 1, s[44:45]
	v_readlane_b32 s44, v255, 28
	v_readlane_b32 s45, v255, 29
	v_cndmask_b32_e64 v45, v45, v46, s[42:43]
	s_movk_i32 s4, 0x48
	v_cndmask_b32_e64 v46, 0, 1, s[44:45]
	v_readlane_b32 s44, v255, 26
	v_readlane_b32 s45, v255, 27
	s_lshl_b32 s95, s1, 1
	s_mov_b32 s72, 0
	v_cndmask_b32_e64 v47, 0, 1, s[44:45]
	v_readlane_b32 s44, v255, 32
	v_readlane_b32 s45, v255, 33
	v_cndmask_b32_e64 v46, v46, v47, s[42:43]
	v_mov_b32_e32 v50, v40
	v_cndmask_b32_e64 v47, 0, 1, s[44:45]
	v_readlane_b32 s44, v255, 30
	v_readlane_b32 s45, v255, 31
	v_mov_b32_e32 v51, v40
	v_mov_b32_e32 v52, v40
	v_cndmask_b32_e64 v48, 0, 1, s[44:45]
	v_readlane_b32 s44, v255, 36
	v_readlane_b32 s45, v255, 37
	v_cndmask_b32_e64 v47, v47, v48, s[42:43]
	v_mov_b32_e32 v53, v40
	v_cndmask_b32_e64 v48, 0, 1, s[44:45]
	v_readlane_b32 s44, v255, 34
	v_readlane_b32 s45, v255, 35
	v_mov_b32_e32 v54, v40
	v_mov_b32_e32 v55, v40
	v_cndmask_b32_e64 v49, 0, 1, s[44:45]
	v_cmp_eq_u32_e64 s[44:45], 1, v41
	v_and_b32_e32 v41, 1, v42
	v_cmp_eq_u32_e64 s[46:47], 1, v41
	v_and_b32_e32 v41, 1, v43
	v_cmp_eq_u32_e64 s[48:49], 1, v41
	v_and_b32_e32 v41, 1, v44
	v_cmp_eq_u32_e64 s[50:51], 1, v41
	v_and_b32_e32 v41, 1, v45
	v_cmp_eq_u32_e64 s[52:53], 1, v41
	v_and_b32_e32 v41, 1, v46
	v_cndmask_b32_e64 v48, v48, v49, s[42:43]
	v_cmp_eq_u32_e64 s[54:55], 1, v41
	v_and_b32_e32 v41, 1, v47
	v_cmp_eq_u32_e64 s[56:57], 1, v41
	v_and_b32_e32 v41, 1, v48
	v_cmp_eq_u32_e64 s[58:59], 1, v41
	v_cndmask_b32_e64 v41, 0, 1, s[60:61]
	v_readlane_b32 s60, v255, 40
	v_readlane_b32 s61, v255, 41
	v_mov_b32_e32 v43, v40
	v_mov_b32_e32 v44, v40
	v_cndmask_b32_e64 v42, 0, 1, s[60:61]
	v_cndmask_b32_e64 v41, v42, v41, s[42:43]
	v_and_b32_e32 v41, 1, v41
	v_cmp_eq_u32_e64 s[60:61], 1, v41
	v_cndmask_b32_e64 v41, 0, 1, s[62:63]
	v_readlane_b32 s62, v255, 44
	v_readlane_b32 s63, v255, 45
	v_mov_b32_e32 v45, v40
	v_mov_b32_e32 v46, v40
	v_cndmask_b32_e64 v42, 0, 1, s[62:63]
	v_cndmask_b32_e64 v41, v42, v41, s[42:43]
	v_and_b32_e32 v41, 1, v41
	v_cmp_eq_u32_e64 s[62:63], 1, v41
	v_cndmask_b32_e64 v41, 0, 1, s[64:65]
	v_readlane_b32 s64, v255, 48
	v_readlane_b32 s65, v255, 49
	v_mov_b32_e32 v47, v40
	v_mov_b32_e32 v48, v40
	v_cndmask_b32_e64 v42, 0, 1, s[64:65]
	v_cndmask_b32_e64 v41, v42, v41, s[42:43]
	v_and_b32_e32 v41, 1, v41
	v_cmp_eq_u32_e64 s[64:65], 1, v41
	v_cndmask_b32_e64 v41, 0, 1, s[66:67]
	v_readlane_b32 s66, v255, 52
	v_readlane_b32 s67, v255, 53
	v_mov_b32_e32 v49, v40
	s_nop 0
	v_cndmask_b32_e64 v42, 0, 1, s[66:67]
	v_cndmask_b32_e64 v41, v42, v41, s[42:43]
	v_and_b32_e32 v41, 1, v41
	v_cmp_eq_u32_e64 s[66:67], 1, v41
	v_mov_b32_e32 v41, v40
	v_mov_b32_e32 v42, v40
	v_readfirstlane_b32 vcc_lo, v164
	v_and_b32_e32 v168, 15, v164
	v_bfe_u32 v169, v164, 4, 2
	v_lshlrev_b32_e32 v168, 13, v168
	s_lshr_b32 vcc_lo, vcc_lo, 6
	s_sub_i32 vcc_hi, 11, vcc_lo
	s_cmp_lt_u32 vcc_lo, 4
	s_cselect_b32 vcc_lo, vcc_lo, vcc_hi
	s_lshl_b32 vcc_lo, vcc_lo, 17
	v_lshl_add_u32 v168, v169, 4, v168
	v_add_u32_e32 v168, vcc_lo, v168
	v_mov_b32_e32 v169, 0
	s_add_u32 s90, s90, 0x1800
	s_addc_u32 s91, s91, 0
	v_lshl_add_u64 v[168:169], s[90:91], 0, v[168:169]
	global_load_dwordx4 v[0:3], v[168:169], off
	global_load_dwordx4 v[8:11], v[168:169], off offset:64
	global_load_dwordx4 v[16:19], v[168:169], off offset:128
	global_load_dwordx4 v[24:27], v[168:169], off offset:192
	s_waitcnt vmcnt(0)
	ds_write_b128 v144, v[4:7] offset:34816
	ds_write_b128 v144, v[12:15] offset:43520
	ds_write_b128 v144, v[20:23] offset:52224
	ds_write_b128 v144, v[28:31] offset:60928
	s_branch .LBB0_97
.Lssd_after_y:
	s_waitcnt lgkmcnt(0)
	s_barrier
	v_cvt_pk_bf16_f32 v56, v40, v41
	v_cvt_pk_bf16_f32 v57, v42, v43
	ds_write_b64 v158, v[56:57]
	v_cvt_pk_bf16_f32 v56, v44, v45
	v_cvt_pk_bf16_f32 v57, v46, v47
	s_not_b32 s74, s72
	s_add_i32 s4, s4, -1
	s_add_i32 s72, s72, 1
	ds_write_b64 v158, v[56:57] offset:32
	v_cvt_pk_bf16_f32 v56, v48, v49
	v_cvt_pk_bf16_f32 v57, v50, v51
	s_cmp_eq_u32 s4, 6
	ds_write_b64 v158, v[56:57] offset:64
	v_cvt_pk_bf16_f32 v56, v52, v53
	v_cvt_pk_bf16_f32 v57, v54, v55
	ds_write_b64 v158, v[56:57] offset:96
	s_cbranch_scc1 .LBB0_87

; __device__ __forceinline__ void phase_C1(const Args& a, unsigned char* ws, const int bid, int l, LAS unsigned char* lds, int tid, int wave, int lane) {
;     ...
;             if (wave == 0) {
;                 const int t0 = 2 * lane;
;                 const float d0 = pd0, d1 = pd1;
;                 const float a0 = d0 * Acoef, a1 = d1 * Acoef, pair = a0 + a1; const float incl = wave_incl_scan(pair);
;                 const float tot = __builtin_bit_cast(float, __builtin_amdgcn_readlane(__builtin_bit_cast(int, incl), 63)), excl = incl - pair;
;                 float c0v, c1v, ref;
;                 if (dir == 0) { c0v = excl + a0; c1v = incl; ref = __shfl(c1v, (lane & ~7) + 7); }
;                 else { c0v = tot - excl; c1v = tot - incl + a1; ref = __shfl(c0v, lane & ~7); }
;                 cs[t0] = c0v; cs[t0 + 1] = c1v; dtv[t0] = d0; dtv[t0 + 1] = d1;
;                 wgt[t0] = d0 * __expf(tot - c0v); wgt[t0 + 1] = d1 * __expf(tot - c1v);
;                 ecs[t0] = __expf(c0v); ecs[t0 + 1] = __expf(c1v);
;                 f2dt[t0] = d0 * __expf(ref - c0v); f2dt[t0 + 1] = d1 * __expf(ref - c1v);
;                 if ((lane & 7) == 0) refarr[lane >> 3] = ref;
;                 if (lane == 0) totp[0] = tot;
.LBB0_108:
	v_cndmask_b32_e64 v56, 0, 1, s[24:25]
	v_cmp_ne_u32_e64 s[0:1], 1, v56
	s_andn2_b64 vcc, exec, s[24:25]
	s_cbranch_vccnz .Lssd_ladder
	s_waitcnt vmcnt(8)
	v_mul_f32_e64 v56, v113, -v166
	v_fma_f32 v58, v112, -v166, v56
	v_mov_b32_e32 v59, v161
	s_mov_b64 s[90:91], -1
	v_add_f32_dpp v57, v58, v58 row_shr:1 row_mask:0xf bank_mask:0xf bound_ctrl:1
	s_and_b64 vcc, exec, s[70:71]
	s_nop 0
	v_add_f32_dpp v57, v57, v57 row_shr:2 row_mask:0xf bank_mask:0xf bound_ctrl:1
	s_nop 1
	v_add_f32_dpp v57, v57, v57 row_shr:4 row_mask:0xf bank_mask:0xf bound_ctrl:1
	s_nop 1
	v_add_f32_dpp v57, v57, v57 row_shr:8 row_mask:0xf bank_mask:0xf bound_ctrl:1
	s_nop 1
	v_mov_b32_dpp v59, v57 row_bcast:15 row_mask:0xa bank_mask:0xf bound_ctrl:1
	v_add_f32_e32 v57, v57, v59
	v_mov_b32_e32 v59, v161
	s_nop 1
	v_mov_b32_dpp v59, v57 row_bcast:31 row_mask:0xc bank_mask:0xf bound_ctrl:1
	v_add_f32_e32 v57, v57, v59
	v_sub_f32_e32 v63, v57, v58
	v_readlane_b32 s74, v57, 63
	s_cbranch_vccz .LBB0_111
	s_nop 0
	v_sub_f32_e32 v59, s74, v57
	v_sub_f32_e32 v58, s74, v63
	v_add_f32_e32 v59, v56, v59
	ds_bpermute_b32 v62, v159, v58
	s_mov_b64 s[90:91], 0
	v_mov_b32_e32 v56, v58
	v_mov_b64_e32 v[60:61], v[58:59]

; #define LDS_BARRIER() do { asm volatile("s_waitcnt lgkmcnt(0)" ::: "memory"); __builtin_amdgcn_s_barrier(); asm volatile("" ::: "memory"); } while (0)
; __device__ __forceinline__ void phase_C1(const Args& a, unsigned char* ws, const int bid, int l, LAS unsigned char* lds, int tid, int wave, int lane) {
;     ...
;             LDS_BARRIER();
;             if (step + 1 < 66) SSD_ISSUE(step + 1);
.Lssd_ladder:
	s_waitcnt vmcnt(9)
	ds_write_b128 v145, v[32:35]
	s_waitcnt vmcnt(8)
	ds_write_b128 v145, v[36:39] offset:9216
.LBB0_118:
	s_waitcnt lgkmcnt(0)
	s_barrier
	s_waitcnt vmcnt(4)
	s_cmp_eq_u32 s4, 7
	s_cbranch_scc1 .LBB0_121
	s_add_i32 s74, s5, s72
	s_add_i32 s74, s74, 7
	s_add_i32 s75, s5, s4
	s_cmpk_eq_i32 s4, 0x48
	s_cselect_b32 s76, s3, s74
	s_cselect_b32 s77, s94, s75
	s_and_b64 s[74:75], s[42:43], exec
	s_cselect_b32 s74, s76, s77
	s_lshl_b32 s90, s74, 7
	s_ashr_i32 s91, s90, 31
	s_lshl_b64 s[74:75], s[90:91], 13
	s_add_u32 s76, s68, s74
	s_addc_u32 s77, s93, s75
	s_add_u32 s74, s76, s95
	s_addc_u32 s75, s77, 0
	v_lshl_add_u64 v[56:57], v[106:107], 1, s[74:75]
	v_add_co_u32_e32 v4, vcc, s83, v56
	s_nop 1
	v_addc_co_u32_e32 v5, vcc, 0, v57, vcc
	v_add_co_u32_e32 v12, vcc, s84, v56
	s_add_u32 s74, s76, s38
	s_addc_u32 s75, s77, 0
	v_addc_co_u32_e32 v13, vcc, 0, v57, vcc
	v_add_co_u32_e32 v20, vcc, s85, v56
	s_nop 1
	v_addc_co_u32_e32 v21, vcc, 0, v57, vcc
	v_add_co_u32_e32 v28, vcc, s86, v56
	s_nop 1
	v_addc_co_u32_e32 v29, vcc, 0, v57, vcc
	v_lshl_add_u64 v[32:33], v[104:105], 1, s[74:75]
	v_add_co_u32_e32 v36, vcc, 0x80000, v32
	s_nop 1
	v_addc_co_u32_e32 v37, vcc, 0, v33, vcc
	global_load_dwordx4 v[4:7], v[4:5], off
	global_load_dwordx4 v[12:15], v[12:13], off
	global_load_dwordx4 v[20:23], v[20:21], off
	global_load_dwordx4 v[28:31], v[28:29], off
	global_load_dwordx4 v[32:35], v[32:33], off nt
	global_load_dwordx4 v[36:39], v[36:37], off nt
	s_and_b64 vcc, exec, s[0:1]
	s_cbranch_vccnz .LBB0_121
	v_or_b32_e32 v56, s90, v109
	v_ashrrev_i32_e32 v57, 31, v56
	v_lshlrev_b64 v[58:59], 8, v[56:57]
	v_or_b32_e32 v56, 1, v56
	v_ashrrev_i32_e32 v57, 31, v56
	v_lshlrev_b64 v[56:57], 8, v[56:57]
	v_lshl_add_u64 v[58:59], s[88:89], 0, v[58:59]
	v_lshl_add_u64 v[56:57], s[88:89], 0, v[56:57]
	global_load_dword v112, v[58:59], off
	global_load_dword v113, v[56:57], off

; #define LAS __attribute__((address_space(3)))
; __device__ __forceinline__ void phase_C1(const Args& a, unsigned char* ws, const int bid, int l, LAS unsigned char* lds, int tid, int wave, int lane) {
;     ...
;             for (int i = 0; i < 4; ++i) { *(LAS u32x4*)(L_C + wCB + i * 32 * 272) = pc[i]; *(LAS u32x4*)(L_B + wCB + i * 32 * 272) = pb[i]; }
; #pragma unroll
;             for (int i = 0; i < 2; ++i) *(LAS u32x4*)(L_X + wX + i * 64 * 144) = px[i];
;     ...
;             { const int q = qt * 16 + fr; const float csq = cs[q], eq = ecs[q];
.Lssd_m_section:
	ds_read_b32 v117, v127
	ds_read_b32 v116, v128
	ds_read_b128 v[180:183], v130
	ds_read_b128 v[184:187], v131
	s_waitcnt lgkmcnt(0)
	s_barrier
	s_cmp_eq_u32 s4, 7
	s_cbranch_scc1 .Lssd_nofill
	s_waitcnt vmcnt(9)
	ds_write_b128 v144, v[4:7] offset:34816
	s_waitcnt vmcnt(8)
	ds_write_b128 v144, v[12:15] offset:43520
	s_waitcnt vmcnt(7)
	ds_write_b128 v144, v[20:23] offset:52224
	s_waitcnt vmcnt(6)
	ds_write_b128 v144, v[28:31] offset:60928

; #define LAS __attribute__((address_space(3)))
; __device__ __forceinline__ unsigned cvt_pk_bf16(float lo, float hi) { unsigned r; asm volatile("v_cvt_pk_bf16_f32 %0, %1, %2" : "=v"(r) : "v"(lo), "v"(hi)); return r; }
; #define MFMA16(a, b, c) __builtin_amdgcn_mfma_f32_16x16x32_bf16((a), (b), (c), 0, 0, 0)
; __device__ __forceinline__ void phase_C1(const Args& a, unsigned char* ws, const int bid, int l, LAS unsigned char* lds, int tid, int wave, int lane) {
;     ...
;               { const int k0 = qt * 16 + fq * 4; const f32x4 ck = *(const LAS f32x4*)(cs + k0), dk = *(const LAS f32x4*)(dtv + k0); float m[4];
; #pragma unroll
;                 for (int r = 0; r < 4; ++r) { const int kk = k0 + r; const bool keep = dir == 0 ? (kk <= q) : (kk >= q); m[r] = keep ? gd[r] * __expf(csq - ck[r]) * dk[r] : 0.f; }
;                 u32x2 o; o.x = cvt_pk_bf16(m[0], m[1]); o.y = cvt_pk_bf16(m[2], m[3]);
;                 *(LAS u32x2*)(L_M + q * 272 + k0 * 2) = o; }
;               f32x4 accB[4];
; #pragma unroll
;               for (int j = 0; j < 4; ++j) accB[j] = (f32x4){0.f, 0.f, 0.f, 0.f};
; #pragma unroll
;               for (int s = 0; s < 4; ++s) { const bf16x8 mq = *(const LAS bf16x8*)(L_M + qt * (16 * 272) + rb + s * 64);
;                   s16x4 xlo[4], xhi[4];
; #pragma unroll
;                   for (int pt = 0; pt < 4; ++pt) { xlo[pt] = __builtin_amdgcn_ds_read_tr16_b64_v4i16((LAS s16x4*)(L_X + trXp + (32 * s) * 144 + (32 * (pt >> 1) + 4 * (pt & 1)) * 2));
;                       xhi[pt] = __builtin_amdgcn_ds_read_tr16_b64_v4i16((LAS s16x4*)(L_X + trXp + (32 * s + 4) * 144 + (32 * (pt >> 1) + 4 * (pt & 1)) * 2)); }
;                   __builtin_amdgcn_sched_barrier(0);
; #pragma unroll
;                   for (int pt = 0; pt < 4; ++pt) { const bf16x8 xf = (bf16x8){xlo[pt].x, xlo[pt].y, xlo[pt].z, xlo[pt].w, xhi[pt].x, xhi[pt].y, xhi[pt].z, xhi[pt].w}; accB[pt] = MFMA16(xf, mq, accB[pt]); }
.LBB0_123:
	s_or_b64 exec, exec, s[0:1]
	v_cndmask_b32_e64 v72, v170, v89, s[12:13]
	v_cndmask_b32_e64 v76, v169, v90, s[12:13]
	v_cndmask_b32_e64 v80, v168, v91, s[12:13]
	v_cndmask_b32_e64 v72, v72, v81, s[14:15]
	v_cndmask_b32_e64 v76, v76, v82, s[14:15]
	v_cndmask_b32_e64 v80, v80, v83, s[14:15]
	v_cndmask_b32_e64 v72, v72, v93, s[16:17]
	v_cndmask_b32_e64 v76, v76, v94, s[16:17]
	v_cndmask_b32_e64 v80, v80, v95, s[16:17]
	v_cndmask_b32_e64 v72, v72, v85, s[18:19]
	v_cndmask_b32_e64 v76, v76, v86, s[18:19]
	v_cndmask_b32_e64 v80, v80, v87, s[18:19]
	v_cndmask_b32_e64 v72, v72, v77, s[20:21]
	v_cndmask_b32_e64 v76, v76, v78, s[20:21]
	v_cndmask_b32_e64 v77, v80, v79, s[20:21]
	v_sub_f32_e32 v78, v117, v181
	v_cndmask_b32_e64 v72, v72, v73, s[22:23]
	v_cndmask_b32_e64 v73, v76, v74, s[22:23]
	v_cndmask_b32_e64 v74, v77, v75, s[22:23]
	v_sub_f32_e32 v75, v117, v182
	v_mul_f32_e32 v78, 0x3fb8aa3b, v78
	v_mul_f32_e32 v75, 0x3fb8aa3b, v75
	v_sub_f32_e32 v76, v117, v183
	v_exp_f32_e32 v78, v78
	v_exp_f32_e32 v75, v75
	v_mul_f32_e32 v76, 0x3fb8aa3b, v76
	v_exp_f32_e32 v76, v76
	v_mul_f32_e32 v72, v72, v78
	v_mul_f32_e32 v73, v73, v75
	v_mul_f32_e32 v72, v185, v72
	v_mul_f32_e32 v73, v186, v73
	v_mul_f32_e32 v74, v74, v76
	v_cndmask_b32_e64 v72, 0, v72, s[62:63]
	v_cndmask_b32_e64 v73, 0, v73, s[64:65]
	v_mul_f32_e32 v74, v187, v74
	v_cndmask_b32_e64 v74, 0, v74, s[66:67]
	v_cvt_pk_bf16_f32 v72, v172, v72
	v_cvt_pk_bf16_f32 v73, v73, v74
	ds_write_b64 v155, v[72:73]
	s_orn2_b64 vcc, s[46:47], s[70:71]
	s_or_b64 vcc, vcc, s[10:11]
	s_cbranch_vccz .Lssd_b_skip0
	ds_read_b128 v[72:75], v156
	ds_read_b64_tr_b16 v[76:77], v157
	ds_read_b64_tr_b16 v[78:79], v157 offset:576
	ds_read_b64_tr_b16 v[80:81], v157 offset:32
	ds_read_b64_tr_b16 v[84:85], v157 offset:64
	ds_read_b64_tr_b16 v[88:89], v157 offset:96
	ds_read_b64_tr_b16 v[82:83], v157 offset:608
	ds_read_b64_tr_b16 v[86:87], v157 offset:640
	ds_read_b64_tr_b16 v[90:91], v157 offset:672
	s_waitcnt lgkmcnt(6)
	v_mfma_f32_16x16x32_bf16 v[76:79], v[76:79], v[72:75], 0
	s_waitcnt lgkmcnt(2)
	v_mfma_f32_16x16x32_bf16 v[80:83], v[80:83], v[72:75], 0
	s_waitcnt lgkmcnt(1)
	v_mfma_f32_16x16x32_bf16 v[84:87], v[84:87], v[72:75], 0
	s_waitcnt lgkmcnt(0)
	v_mfma_f32_16x16x32_bf16 v[72:75], v[88:91], v[72:75], 0
	s_branch .Lssd_b_s1

; #define LAS __attribute__((address_space(3)))
; #define MFMA16(a, b, c) __builtin_amdgcn_mfma_f32_16x16x32_bf16((a), (b), (c), 0, 0, 0)
; __device__ __forceinline__ void phase_C1(const Args& a, unsigned char* ws, const int bid, int l, LAS unsigned char* lds, int tid, int wave, int lane) {
;     ...
;               for (int s = 0; s < 4; ++s) { const bf16x8 mq = *(const LAS bf16x8*)(L_M + qt * (16 * 272) + rb + s * 64);
;                   s16x4 xlo[4], xhi[4];
; #pragma unroll
;                   for (int pt = 0; pt < 4; ++pt) { xlo[pt] = __builtin_amdgcn_ds_read_tr16_b64_v4i16((LAS s16x4*)(L_X + trXp + (32 * s) * 144 + (32 * (pt >> 1) + 4 * (pt & 1)) * 2));
;                       xhi[pt] = __builtin_amdgcn_ds_read_tr16_b64_v4i16((LAS s16x4*)(L_X + trXp + (32 * s + 4) * 144 + (32 * (pt >> 1) + 4 * (pt & 1)) * 2)); }
;                   __builtin_amdgcn_sched_barrier(0);
; #pragma unroll
;                   for (int pt = 0; pt < 4; ++pt) { const bf16x8 xf = (bf16x8){xlo[pt].x, xlo[pt].y, xlo[pt].z, xlo[pt].w, xhi[pt].x, xhi[pt].y, xhi[pt].z, xhi[pt].w}; accB[pt] = MFMA16(xf, mq, accB[pt]); }
;                   __builtin_amdgcn_sched_barrier(0); }
.Lssd_b_s1:
	s_or_b64 vcc, s[48:49], s[50:51]
	s_or_b64 vcc, vcc, s[12:13]
	s_or_b64 vcc, vcc, s[14:15]
	s_cbranch_vccz .Lssd_b_s2
	ds_read_b128 v[88:91], v156 offset:64
	ds_read_b64_tr_b16 v[92:93], v157 offset:4608
	ds_read_b64_tr_b16 v[94:95], v157 offset:5184
	ds_read_b64_tr_b16 v[96:97], v157 offset:4640
	ds_read_b64_tr_b16 v[100:101], v157 offset:4672
	ds_read_b64_tr_b16 v[168:169], v157 offset:4704
	ds_read_b64_tr_b16 v[98:99], v157 offset:5216
	ds_read_b64_tr_b16 v[102:103], v157 offset:5248
	ds_read_b64_tr_b16 v[170:171], v157 offset:5280
	s_waitcnt lgkmcnt(6)
	v_mfma_f32_16x16x32_bf16 v[76:79], v[92:95], v[88:91], v[76:79]
	s_waitcnt lgkmcnt(2)
	v_mfma_f32_16x16x32_bf16 v[80:83], v[96:99], v[88:91], v[80:83]
	s_waitcnt lgkmcnt(0)
	v_mfma_f32_16x16x32_bf16 v[72:75], v[168:171], v[88:91], v[72:75]
	v_mfma_f32_16x16x32_bf16 v[84:87], v[100:103], v[88:91], v[84:87]
.Lssd_b_s2:
	s_or_b64 vcc, s[52:53], s[54:55]
	s_or_b64 vcc, vcc, s[16:17]
	s_or_b64 vcc, vcc, s[18:19]
	s_cbranch_vccz .Lssd_b_s3
	ds_read_b128 v[88:91], v156 offset:128
	ds_read_b64_tr_b16 v[92:93], v157 offset:9216
	ds_read_b64_tr_b16 v[94:95], v157 offset:9792
	ds_read_b64_tr_b16 v[96:97], v157 offset:9248
	ds_read_b64_tr_b16 v[100:101], v157 offset:9280
	ds_read_b64_tr_b16 v[168:169], v157 offset:9312
	ds_read_b64_tr_b16 v[98:99], v157 offset:9824
	ds_read_b64_tr_b16 v[102:103], v157 offset:9856
	ds_read_b64_tr_b16 v[170:171], v157 offset:9888
	s_waitcnt lgkmcnt(6)
	v_mfma_f32_16x16x32_bf16 v[76:79], v[92:95], v[88:91], v[76:79]
	s_waitcnt lgkmcnt(2)
	v_mfma_f32_16x16x32_bf16 v[80:83], v[96:99], v[88:91], v[80:83]
	s_waitcnt lgkmcnt(0)
	v_mfma_f32_16x16x32_bf16 v[72:75], v[168:171], v[88:91], v[72:75]
	v_mfma_f32_16x16x32_bf16 v[84:87], v[100:103], v[88:91], v[84:87]
.Lssd_b_s3:
	s_or_b64 vcc, s[56:57], s[58:59]
	s_or_b64 vcc, vcc, s[20:21]
	s_or_b64 vcc, vcc, s[22:23]
	s_cbranch_vccz .Lssd_b_skip3
	ds_read_b128 v[88:91], v156 offset:192
	ds_read_b64_tr_b16 v[92:93], v157 offset:13824
	ds_read_b64_tr_b16 v[94:95], v157 offset:14400
	ds_read_b64_tr_b16 v[96:97], v157 offset:13856
	ds_read_b64_tr_b16 v[100:101], v157 offset:13888
	ds_read_b64_tr_b16 v[168:169], v157 offset:13920
	ds_read_b64_tr_b16 v[98:99], v157 offset:14432
	ds_read_b64_tr_b16 v[102:103], v157 offset:14464
	ds_read_b64_tr_b16 v[170:171], v157 offset:14496
	s_waitcnt lgkmcnt(6)
	v_mfma_f32_16x16x32_bf16 v[92:95], v[92:95], v[88:91], v[76:79]
	s_waitcnt lgkmcnt(1)
	v_mfma_f32_16x16x32_bf16 v[76:79], v[100:103], v[88:91], v[84:87]
	s_waitcnt lgkmcnt(0)
	v_mfma_f32_16x16x32_bf16 v[72:75], v[168:171], v[88:91], v[72:75]
	v_mfma_f32_16x16x32_bf16 v[96:99], v[96:99], v[88:91], v[80:83]
	s_branch .Lssd_b_done

; #define LAS __attribute__((address_space(3)))
; __device__ __forceinline__ void phase_C1(const Args& a, unsigned char* ws, const int bid, int l, LAS unsigned char* lds, int tid, int wave, int lane) {
;     ...
;               bf16_t* yrow = z + (size_t)(row0 + q) * ZW + dir * 2048 + h * 64 + 8 * fq;
; #pragma unroll
;               for (int m = 0; m < 2; ++m) { float y[8];
; #pragma unroll
;                   for (int r = 0; r < 4; ++r) { y[r] = accB[2 * m][r] + eq * accC[2 * m][r]; y[4 + r] = accB[2 * m + 1][r] + eq * accC[2 * m + 1][r]; }
;                   if (dir == 0) { const u32x4 xv = *(const LAS u32x4*)(L_X + q * 144 + (32 * m + 8 * fq) * 2); float xf8[8]; unpack8(xv, xf8);
; #pragma unroll
;                       for (int e = 0; e < 8; ++e) y[e] += dskip * xf8[e]; }
;                   *(u32x4*)(yrow + 32 * m) = pack8(y); } }
.Lssd_b_done:
	s_nop 7
	v_mov_b32_e32 v117, v116
	v_pk_fma_f32 v[68:69], v[68:69], v[116:117], v[92:93]
	v_pk_fma_f32 v[70:71], v[70:71], v[116:117], v[94:95]
	v_pk_fma_f32 v[64:65], v[64:65], v[116:117], v[96:97]
	v_pk_fma_f32 v[66:67], v[66:67], v[116:117], v[98:99]
	v_pk_fma_f32 v[60:61], v[60:61], v[116:117], v[76:77]
	v_pk_fma_f32 v[62:63], v[62:63], v[116:117], v[78:79]
	v_pk_fma_f32 v[56:57], v[56:57], v[116:117], v[72:73]
	v_pk_fma_f32 v[58:59], v[58:59], v[116:117], v[74:75]
	v_bfe_u32 v90, v164, 4, 2
	v_lshlrev_b32_e32 v90, 3, v90
	v_lshl_add_u32 v91, s73, 7, v126
	v_mad_i64_i32 v[88:89], s[74:75], v91, s2, v[114:115]
	v_mov_b32_e32 v91, 0
	v_sub_co_u32_e32 v88, vcc, v88, v90
	s_nop 1
	v_subb_co_u32_e32 v89, vcc, v89, v91, vcc
	s_andn2_b64 vcc, exec, s[42:43]
	s_cbranch_vccnz .Lssd_y_pack
	v_sub_u32_e32 v91, v165, v90
	ds_read_b64 v[80:81], v91
	ds_read_b64 v[82:83], v91 offset:32
	ds_read_b64 v[84:85], v91 offset:64
	ds_read_b64 v[86:87], v91 offset:96
	s_waitcnt lgkmcnt(0)
	v_lshlrev_b32_e32 v92, 16, v80
	v_and_b32_e32 v93, 0xffff0000, v80
	v_pk_fma_f32 v[68:69], v[110:111], v[92:93], v[68:69]
	v_lshlrev_b32_e32 v92, 16, v81
	v_and_b32_e32 v93, 0xffff0000, v81
	v_pk_fma_f32 v[70:71], v[110:111], v[92:93], v[70:71]
	v_lshlrev_b32_e32 v92, 16, v82
	v_and_b32_e32 v93, 0xffff0000, v82
	v_pk_fma_f32 v[64:65], v[110:111], v[92:93], v[64:65]
	v_lshlrev_b32_e32 v92, 16, v83
	v_and_b32_e32 v93, 0xffff0000, v83
	v_pk_fma_f32 v[66:67], v[110:111], v[92:93], v[66:67]
	v_lshlrev_b32_e32 v92, 16, v84
	v_and_b32_e32 v93, 0xffff0000, v84
	v_pk_fma_f32 v[60:61], v[110:111], v[92:93], v[60:61]
	v_lshlrev_b32_e32 v92, 16, v85
	v_and_b32_e32 v93, 0xffff0000, v85
	v_pk_fma_f32 v[62:63], v[110:111], v[92:93], v[62:63]
	v_lshlrev_b32_e32 v92, 16, v86
	v_and_b32_e32 v93, 0xffff0000, v86
	v_pk_fma_f32 v[56:57], v[110:111], v[92:93], v[56:57]
	v_lshlrev_b32_e32 v92, 16, v87
	v_and_b32_e32 v93, 0xffff0000, v87
	v_pk_fma_f32 v[58:59], v[110:111], v[92:93], v[58:59]
.Lssd_y_pack:
	v_cvt_pk_bf16_f32 v80, v68, v69
	v_cvt_pk_bf16_f32 v81, v70, v71
	global_store_dwordx2 v[88:89], v[80:81], off
	v_cvt_pk_bf16_f32 v82, v64, v65
	v_cvt_pk_bf16_f32 v83, v66, v67
	global_store_dwordx2 v[88:89], v[82:83], off offset:32
	v_cvt_pk_bf16_f32 v84, v60, v61
	v_cvt_pk_bf16_f32 v85, v62, v63
	global_store_dwordx2 v[88:89], v[84:85], off offset:64
	v_cvt_pk_bf16_f32 v86, v56, v57
	v_cvt_pk_bf16_f32 v87, v58, v59
	global_store_dwordx2 v[88:89], v[86:87], off offset:96
	s_branch .Lssd_after_y

; #define MFMA16(a, b, c) __builtin_amdgcn_mfma_f32_16x16x32_bf16((a), (b), (c), 0, 0, 0)
; __device__ __forceinline__ void phase_C1(const Args& a, unsigned char* ws, const int bid, int l, LAS unsigned char* lds, int tid, int wave, int lane) {
;     ...
;             {
;                 bf16x8 cqv[2], bq[2][4], hq[2][2];
;     ...
;                 SSD_LDH(0, 0);
; #pragma unroll
;                 for (int h2 = 0; h2 < 8; ++h2) { const int cb = h2 & 1, s_ = h2 >> 1, hf_ = h2 & 1;
;                     if (h2 < 7) SSD_LDH(cb ^ 1, h2 + 1);
;                     __builtin_amdgcn_sched_barrier(0);
; #pragma unroll
;                     for (int k = 0; k < 4; ++k) accA[4 * hf_ + k] = MFMA16(bq[cb][k], cqv[s_ & 1], accA[4 * hf_ + k]);
; #pragma unroll
;                     for (int p = 0; p < 2; ++p) accC[2 * hf_ + p] = MFMA16(hq[cb][p], cqv[s_ & 1], accC[2 * hf_ + p]);
;                     __builtin_amdgcn_sched_barrier(0); }
.Lssd_A_1111:
	ds_read_b128 v[56:59], v118 offset:34816
	ds_read_b128 v[60:63], v118 offset:39168
	ds_read_b128 v[64:67], v118 offset:43520
	ds_read_b128 v[68:71], v118 offset:47872
	ds_read_b128 v[76:79], v147
	ds_read_b128 v[80:83], v118 offset:52224
	ds_read_b128 v[84:87], v118 offset:56576
	ds_read_b128 v[88:91], v118 offset:60928
	ds_read_b128 v[92:95], v118 offset:65280
	ds_read_b128 v[96:99], v147 offset:4352
	ds_read_b128 v[100:103], v147 offset:8704
	ds_read_b128 v[168:171], v147 offset:13056
	s_waitcnt lgkmcnt(11)
	v_mfma_f32_16x16x32_bf16 v[56:59], v[56:59], v[0:3], 0
	s_waitcnt lgkmcnt(10)
	v_mfma_f32_16x16x32_bf16 v[60:63], v[60:63], v[0:3], 0
	s_waitcnt lgkmcnt(9)
	v_mfma_f32_16x16x32_bf16 v[64:67], v[64:67], v[0:3], 0
	s_waitcnt lgkmcnt(8)
	v_mfma_f32_16x16x32_bf16 v[68:71], v[68:71], v[0:3], 0
	s_waitcnt lgkmcnt(7)
	v_mfma_f32_16x16x32_bf16 v[76:79], v[76:79], v[0:3], 0
	s_waitcnt lgkmcnt(2)
	v_mfma_f32_16x16x32_bf16 v[96:99], v[96:99], v[0:3], 0
	ds_read_b128 v[172:175], v118 offset:34880
	ds_read_b128 v[176:179], v118 offset:39232
	ds_read_b128 v[180:183], v118 offset:43584
	ds_read_b128 v[184:187], v118 offset:47936
	ds_read_b128 v[212:215], v147 offset:64
	ds_read_b128 v[216:219], v147 offset:4416
	v_mfma_f32_16x16x32_bf16 v[80:83], v[80:83], v[0:3], 0
	v_mfma_f32_16x16x32_bf16 v[84:87], v[84:87], v[0:3], 0
	v_mfma_f32_16x16x32_bf16 v[88:91], v[88:91], v[0:3], 0
	v_mfma_f32_16x16x32_bf16 v[92:95], v[92:95], v[0:3], 0
	s_waitcnt lgkmcnt(7)
	v_mfma_f32_16x16x32_bf16 v[100:103], v[100:103], v[0:3], 0
	s_waitcnt lgkmcnt(6)
	v_mfma_f32_16x16x32_bf16 v[72:75], v[168:171], v[0:3], 0
	ds_read_b128 v[168:171], v118 offset:52288
	ds_read_b128 v[220:223], v118 offset:56640
	ds_read_b128 v[224:227], v118 offset:60992
	ds_read_b128 v[228:231], v118 offset:65344
	ds_read_b128 v[232:235], v147 offset:8768
	ds_read_b128 v[236:239], v147 offset:13120
	s_waitcnt lgkmcnt(11)
	v_mfma_f32_16x16x32_bf16 v[56:59], v[172:175], v[8:11], v[56:59]
	s_waitcnt lgkmcnt(10)
	v_mfma_f32_16x16x32_bf16 v[60:63], v[176:179], v[8:11], v[60:63]
	s_waitcnt lgkmcnt(9)
	v_mfma_f32_16x16x32_bf16 v[64:67], v[180:183], v[8:11], v[64:67]
	s_waitcnt lgkmcnt(8)
	v_mfma_f32_16x16x32_bf16 v[68:71], v[184:187], v[8:11], v[68:71]
	s_waitcnt lgkmcnt(7)
	v_mfma_f32_16x16x32_bf16 v[76:79], v[212:215], v[8:11], v[76:79]
	s_waitcnt lgkmcnt(6)
	v_mfma_f32_16x16x32_bf16 v[96:99], v[216:219], v[8:11], v[96:99]
	ds_read_b128 v[172:175], v118 offset:34944
	ds_read_b128 v[176:179], v118 offset:39296
	ds_read_b128 v[180:183], v118 offset:43648
	ds_read_b128 v[184:187], v118 offset:48000
	ds_read_b128 v[216:219], v147 offset:128
	ds_read_b128 v[240:243], v147 offset:4480
	s_waitcnt lgkmcnt(11)
	v_mfma_f32_16x16x32_bf16 v[80:83], v[168:171], v[8:11], v[80:83]
	s_waitcnt lgkmcnt(10)
	v_mfma_f32_16x16x32_bf16 v[84:87], v[220:223], v[8:11], v[84:87]
	s_waitcnt lgkmcnt(9)
	v_mfma_f32_16x16x32_bf16 v[88:91], v[224:227], v[8:11], v[88:91]
	s_waitcnt lgkmcnt(8)
	v_mfma_f32_16x16x32_bf16 v[92:95], v[228:231], v[8:11], v[92:95]
	s_waitcnt lgkmcnt(7)
	v_mfma_f32_16x16x32_bf16 v[100:103], v[232:235], v[8:11], v[100:103]
	s_waitcnt lgkmcnt(6)
	v_mfma_f32_16x16x32_bf16 v[72:75], v[236:239], v[8:11], v[72:75]
	ds_read_b128 v[168:171], v118 offset:52352
	ds_read_b128 v[188:191], v118 offset:56704
	ds_read_b128 v[220:223], v118 offset:61056
	ds_read_b128 v[224:227], v118 offset:65408
	ds_read_b128 v[228:231], v147 offset:8832
	ds_read_b128 v[232:235], v147 offset:13184
	s_waitcnt lgkmcnt(11)
	v_mfma_f32_16x16x32_bf16 v[56:59], v[172:175], v[16:19], v[56:59]
	s_waitcnt lgkmcnt(10)
	v_mfma_f32_16x16x32_bf16 v[60:63], v[176:179], v[16:19], v[60:63]
	s_waitcnt lgkmcnt(9)
	v_mfma_f32_16x16x32_bf16 v[64:67], v[180:183], v[16:19], v[64:67]
	s_waitcnt lgkmcnt(8)
	v_mfma_f32_16x16x32_bf16 v[68:71], v[184:187], v[16:19], v[68:71]
	s_waitcnt lgkmcnt(7)
	v_mfma_f32_16x16x32_bf16 v[76:79], v[216:219], v[16:19], v[76:79]
	s_waitcnt lgkmcnt(6)
	v_mfma_f32_16x16x32_bf16 v[172:175], v[240:243], v[16:19], v[96:99]
	s_nop 2
	ds_read_b128 v[96:99], v118 offset:35008
	ds_read_b128 v[176:179], v118 offset:39360
	ds_read_b128 v[180:183], v118 offset:43712
	ds_read_b128 v[184:187], v118 offset:48064
	ds_read_b128 v[236:239], v147 offset:192
	ds_read_b128 v[240:243], v147 offset:4544
	s_waitcnt lgkmcnt(11)
	v_mfma_f32_16x16x32_bf16 v[168:171], v[168:171], v[16:19], v[80:83]
	s_waitcnt lgkmcnt(10)
	v_mfma_f32_16x16x32_bf16 v[84:87], v[188:191], v[16:19], v[84:87]
	s_waitcnt lgkmcnt(9)
	v_mfma_f32_16x16x32_bf16 v[188:191], v[220:223], v[16:19], v[88:91]
	s_waitcnt lgkmcnt(8)
	v_mfma_f32_16x16x32_bf16 v[220:223], v[224:227], v[16:19], v[92:95]
	s_waitcnt lgkmcnt(7)
	v_mfma_f32_16x16x32_bf16 v[224:227], v[228:231], v[16:19], v[100:103]
	s_waitcnt lgkmcnt(6)
	v_mfma_f32_16x16x32_bf16 v[212:215], v[232:235], v[16:19], v[72:75]
	s_nop 2
	ds_read_b128 v[72:75], v118 offset:52416
	ds_read_b128 v[228:231], v118 offset:56768
	ds_read_b128 v[232:235], v118 offset:61120
	ds_read_b128 v[244:247], v118 offset:65472
	ds_read_b128 v[248:251], v147 offset:8896
	ds_read_b128 v[192:195], v147 offset:13248
	s_waitcnt lgkmcnt(11)
	v_mfma_f32_16x16x32_bf16 v[100:103], v[96:99], v[24:27], v[56:59]
	s_waitcnt lgkmcnt(10)
	v_mfma_f32_16x16x32_bf16 v[96:99], v[176:179], v[24:27], v[60:63]
	s_waitcnt lgkmcnt(9)
	v_mfma_f32_16x16x32_bf16 v[88:91], v[180:183], v[24:27], v[64:67]
	s_waitcnt lgkmcnt(8)
	v_mfma_f32_16x16x32_bf16 v[80:83], v[184:187], v[24:27], v[68:71]
	s_waitcnt lgkmcnt(7)
	v_mfma_f32_16x16x32_bf16 v[68:71], v[236:239], v[24:27], v[76:79]
	s_waitcnt lgkmcnt(6)
	v_mfma_f32_16x16x32_bf16 v[64:67], v[240:243], v[24:27], v[172:175]
	s_waitcnt lgkmcnt(5)
	v_mfma_f32_16x16x32_bf16 v[92:95], v[72:75], v[24:27], v[168:171]
	s_waitcnt lgkmcnt(4)
	v_mfma_f32_16x16x32_bf16 v[84:87], v[228:231], v[24:27], v[84:87]
	s_waitcnt lgkmcnt(3)
	v_mfma_f32_16x16x32_bf16 v[76:79], v[232:235], v[24:27], v[188:191]
	s_waitcnt lgkmcnt(2)
	v_mfma_f32_16x16x32_bf16 v[72:75], v[244:247], v[24:27], v[220:223]
	s_waitcnt lgkmcnt(1)
	v_mfma_f32_16x16x32_bf16 v[60:63], v[248:251], v[24:27], v[224:227]
	s_waitcnt lgkmcnt(0)
	v_mfma_f32_16x16x32_bf16 v[56:59], v[192:195], v[24:27], v[212:215]
	s_branch .Lssd_A_join
; #define MFMA16(a, b, c) __builtin_amdgcn_mfma_f32_16x16x32_bf16((a), (b), (c), 0, 0, 0)
; __device__ __forceinline__ void phase_C1(const Args& a, unsigned char* ws, const int bid, int l, LAS unsigned char* lds, int tid, int wave, int lane) {
;     ...
;             {
;                 bf16x8 cqv[2], bq[2][4], hq[2][2];
;     ...
;                 SSD_LDH(0, 0);
; #pragma unroll
;                 for (int h2 = 0; h2 < 8; ++h2) { const int cb = h2 & 1, s_ = h2 >> 1, hf_ = h2 & 1;
;                     if (h2 < 7) SSD_LDH(cb ^ 1, h2 + 1);
;                     __builtin_amdgcn_sched_barrier(0);
; #pragma unroll
;                     for (int k = 0; k < 4; ++k) accA[4 * hf_ + k] = MFMA16(bq[cb][k], cqv[s_ & 1], accA[4 * hf_ + k]);
; #pragma unroll
;                     for (int p = 0; p < 2; ++p) accC[2 * hf_ + p] = MFMA16(hq[cb][p], cqv[s_ & 1], accC[2 * hf_ + p]);
;                     __builtin_amdgcn_sched_barrier(0); }
.Lssd_A_1000:
	ds_read_b128 v[56:59], v118 offset:34816
	ds_read_b128 v[60:63], v118 offset:39168
	ds_read_b128 v[76:79], v147
	ds_read_b128 v[96:99], v147 offset:4352
	ds_read_b128 v[100:103], v147 offset:8704
	ds_read_b128 v[168:171], v147 offset:13056
	s_waitcnt lgkmcnt(5)
	v_mfma_f32_16x16x32_bf16 v[56:59], v[56:59], v[0:3], 0
	s_waitcnt lgkmcnt(4)
	v_mfma_f32_16x16x32_bf16 v[60:63], v[60:63], v[0:3], 0
	s_waitcnt lgkmcnt(3)
	v_mfma_f32_16x16x32_bf16 v[76:79], v[76:79], v[0:3], 0
	s_waitcnt lgkmcnt(2)
	v_mfma_f32_16x16x32_bf16 v[96:99], v[96:99], v[0:3], 0
	ds_read_b128 v[172:175], v118 offset:34880
	ds_read_b128 v[176:179], v118 offset:39232
	ds_read_b128 v[212:215], v147 offset:64
	ds_read_b128 v[216:219], v147 offset:4416
	s_waitcnt lgkmcnt(5)
	v_mfma_f32_16x16x32_bf16 v[100:103], v[100:103], v[0:3], 0
	s_waitcnt lgkmcnt(4)
	v_mfma_f32_16x16x32_bf16 v[72:75], v[168:171], v[0:3], 0
	ds_read_b128 v[232:235], v147 offset:8768
	ds_read_b128 v[236:239], v147 offset:13120
	s_waitcnt lgkmcnt(5)
	v_mfma_f32_16x16x32_bf16 v[56:59], v[172:175], v[8:11], v[56:59]
	s_waitcnt lgkmcnt(4)
	v_mfma_f32_16x16x32_bf16 v[60:63], v[176:179], v[8:11], v[60:63]
	s_waitcnt lgkmcnt(3)
	v_mfma_f32_16x16x32_bf16 v[76:79], v[212:215], v[8:11], v[76:79]
	s_waitcnt lgkmcnt(2)
	v_mfma_f32_16x16x32_bf16 v[96:99], v[216:219], v[8:11], v[96:99]
	ds_read_b128 v[172:175], v118 offset:34944
	ds_read_b128 v[176:179], v118 offset:39296
	ds_read_b128 v[216:219], v147 offset:128
	ds_read_b128 v[240:243], v147 offset:4480
	s_waitcnt lgkmcnt(5)
	v_mfma_f32_16x16x32_bf16 v[100:103], v[232:235], v[8:11], v[100:103]
	s_waitcnt lgkmcnt(4)
	v_mfma_f32_16x16x32_bf16 v[72:75], v[236:239], v[8:11], v[72:75]
	ds_read_b128 v[228:231], v147 offset:8832
	ds_read_b128 v[232:235], v147 offset:13184
	s_waitcnt lgkmcnt(5)
	v_mfma_f32_16x16x32_bf16 v[56:59], v[172:175], v[16:19], v[56:59]
	s_waitcnt lgkmcnt(4)
	v_mfma_f32_16x16x32_bf16 v[60:63], v[176:179], v[16:19], v[60:63]
	s_waitcnt lgkmcnt(3)
	v_mfma_f32_16x16x32_bf16 v[76:79], v[216:219], v[16:19], v[76:79]
	s_waitcnt lgkmcnt(2)
	v_mfma_f32_16x16x32_bf16 v[172:175], v[240:243], v[16:19], v[96:99]
	s_nop 2
	ds_read_b128 v[96:99], v118 offset:35008
	ds_read_b128 v[176:179], v118 offset:39360
	ds_read_b128 v[236:239], v147 offset:192
	ds_read_b128 v[240:243], v147 offset:4544
	s_waitcnt lgkmcnt(5)
	v_mfma_f32_16x16x32_bf16 v[224:227], v[228:231], v[16:19], v[100:103]
	s_waitcnt lgkmcnt(4)
	v_mfma_f32_16x16x32_bf16 v[212:215], v[232:235], v[16:19], v[72:75]
	s_nop 2
	ds_read_b128 v[248:251], v147 offset:8896
	ds_read_b128 v[192:195], v147 offset:13248
	s_waitcnt lgkmcnt(5)
	v_mfma_f32_16x16x32_bf16 v[100:103], v[96:99], v[24:27], v[56:59]
	s_waitcnt lgkmcnt(4)
	v_mfma_f32_16x16x32_bf16 v[96:99], v[176:179], v[24:27], v[60:63]
	s_waitcnt lgkmcnt(3)
	v_mfma_f32_16x16x32_bf16 v[68:71], v[236:239], v[24:27], v[76:79]
	s_waitcnt lgkmcnt(2)
	v_mfma_f32_16x16x32_bf16 v[64:67], v[240:243], v[24:27], v[172:175]
	s_waitcnt lgkmcnt(1)
	v_mfma_f32_16x16x32_bf16 v[60:63], v[248:251], v[24:27], v[224:227]
	s_waitcnt lgkmcnt(0)
	v_mfma_f32_16x16x32_bf16 v[56:59], v[192:195], v[24:27], v[212:215]
	s_branch .Lssd_A_join
.Lssd_A_1100:
	ds_read_b128 v[56:59], v118 offset:34816
	ds_read_b128 v[60:63], v118 offset:39168
	ds_read_b128 v[64:67], v118 offset:43520
	ds_read_b128 v[68:71], v118 offset:47872
	ds_read_b128 v[76:79], v147
	ds_read_b128 v[96:99], v147 offset:4352
	ds_read_b128 v[100:103], v147 offset:8704
	ds_read_b128 v[168:171], v147 offset:13056
	s_waitcnt lgkmcnt(7)
	v_mfma_f32_16x16x32_bf16 v[56:59], v[56:59], v[0:3], 0
	s_waitcnt lgkmcnt(6)
	v_mfma_f32_16x16x32_bf16 v[60:63], v[60:63], v[0:3], 0
	s_waitcnt lgkmcnt(5)
	v_mfma_f32_16x16x32_bf16 v[64:67], v[64:67], v[0:3], 0
	s_waitcnt lgkmcnt(4)
	v_mfma_f32_16x16x32_bf16 v[68:71], v[68:71], v[0:3], 0
	s_waitcnt lgkmcnt(3)
	v_mfma_f32_16x16x32_bf16 v[76:79], v[76:79], v[0:3], 0
	s_waitcnt lgkmcnt(2)
	v_mfma_f32_16x16x32_bf16 v[96:99], v[96:99], v[0:3], 0
	ds_read_b128 v[172:175], v118 offset:34880
	ds_read_b128 v[176:179], v118 offset:39232
	ds_read_b128 v[180:183], v118 offset:43584
	ds_read_b128 v[184:187], v118 offset:47936
	ds_read_b128 v[212:215], v147 offset:64
	ds_read_b128 v[216:219], v147 offset:4416
	s_waitcnt lgkmcnt(7)
	v_mfma_f32_16x16x32_bf16 v[100:103], v[100:103], v[0:3], 0
	s_waitcnt lgkmcnt(6)
	v_mfma_f32_16x16x32_bf16 v[72:75], v[168:171], v[0:3], 0
	ds_read_b128 v[232:235], v147 offset:8768
	ds_read_b128 v[236:239], v147 offset:13120
	s_waitcnt lgkmcnt(7)
	v_mfma_f32_16x16x32_bf16 v[56:59], v[172:175], v[8:11], v[56:59]
	s_waitcnt lgkmcnt(6)
	v_mfma_f32_16x16x32_bf16 v[60:63], v[176:179], v[8:11], v[60:63]
	s_waitcnt lgkmcnt(5)
	v_mfma_f32_16x16x32_bf16 v[64:67], v[180:183], v[8:11], v[64:67]
	s_waitcnt lgkmcnt(4)
	v_mfma_f32_16x16x32_bf16 v[68:71], v[184:187], v[8:11], v[68:71]
	s_waitcnt lgkmcnt(3)
	v_mfma_f32_16x16x32_bf16 v[76:79], v[212:215], v[8:11], v[76:79]
	s_waitcnt lgkmcnt(2)
	v_mfma_f32_16x16x32_bf16 v[96:99], v[216:219], v[8:11], v[96:99]
	ds_read_b128 v[172:175], v118 offset:34944
	ds_read_b128 v[176:179], v118 offset:39296
	ds_read_b128 v[180:183], v118 offset:43648
	ds_read_b128 v[184:187], v118 offset:48000
	ds_read_b128 v[216:219], v147 offset:128
	ds_read_b128 v[240:243], v147 offset:4480
	s_waitcnt lgkmcnt(7)
	v_mfma_f32_16x16x32_bf16 v[100:103], v[232:235], v[8:11], v[100:103]
	s_waitcnt lgkmcnt(6)
	v_mfma_f32_16x16x32_bf16 v[72:75], v[236:239], v[8:11], v[72:75]
	ds_read_b128 v[228:231], v147 offset:8832
	ds_read_b128 v[232:235], v147 offset:13184
	s_waitcnt lgkmcnt(7)
	v_mfma_f32_16x16x32_bf16 v[56:59], v[172:175], v[16:19], v[56:59]
	s_waitcnt lgkmcnt(6)
; #define MFMA16(a, b, c) __builtin_amdgcn_mfma_f32_16x16x32_bf16((a), (b), (c), 0, 0, 0)
; __device__ __forceinline__ void phase_C1(const Args& a, unsigned char* ws, const int bid, int l, LAS unsigned char* lds, int tid, int wave, int lane) {
;     ...
;             {
;                 bf16x8 cqv[2], bq[2][4], hq[2][2];
;     ...
;                 SSD_LDH(0, 0);
; #pragma unroll
;                 for (int h2 = 0; h2 < 8; ++h2) { const int cb = h2 & 1, s_ = h2 >> 1, hf_ = h2 & 1;
;                     if (h2 < 7) SSD_LDH(cb ^ 1, h2 + 1);
;                     __builtin_amdgcn_sched_barrier(0);
; #pragma unroll
;                     for (int k = 0; k < 4; ++k) accA[4 * hf_ + k] = MFMA16(bq[cb][k], cqv[s_ & 1], accA[4 * hf_ + k]);
; #pragma unroll
;                     for (int p = 0; p < 2; ++p) accC[2 * hf_ + p] = MFMA16(hq[cb][p], cqv[s_ & 1], accC[2 * hf_ + p]);
;                     __builtin_amdgcn_sched_barrier(0); }
	v_mfma_f32_16x16x32_bf16 v[60:63], v[176:179], v[16:19], v[60:63]
	s_waitcnt lgkmcnt(5)
	v_mfma_f32_16x16x32_bf16 v[64:67], v[180:183], v[16:19], v[64:67]
	s_waitcnt lgkmcnt(4)
	v_mfma_f32_16x16x32_bf16 v[68:71], v[184:187], v[16:19], v[68:71]
	s_waitcnt lgkmcnt(3)
	v_mfma_f32_16x16x32_bf16 v[76:79], v[216:219], v[16:19], v[76:79]
	s_waitcnt lgkmcnt(2)
	v_mfma_f32_16x16x32_bf16 v[172:175], v[240:243], v[16:19], v[96:99]
	s_nop 2
	ds_read_b128 v[96:99], v118 offset:35008
	ds_read_b128 v[176:179], v118 offset:39360
	ds_read_b128 v[180:183], v118 offset:43712
	ds_read_b128 v[184:187], v118 offset:48064
	ds_read_b128 v[236:239], v147 offset:192
	ds_read_b128 v[240:243], v147 offset:4544
	s_waitcnt lgkmcnt(7)
	v_mfma_f32_16x16x32_bf16 v[224:227], v[228:231], v[16:19], v[100:103]
	s_waitcnt lgkmcnt(6)
	v_mfma_f32_16x16x32_bf16 v[212:215], v[232:235], v[16:19], v[72:75]
	s_nop 2
	ds_read_b128 v[248:251], v147 offset:8896
	ds_read_b128 v[192:195], v147 offset:13248
	s_waitcnt lgkmcnt(7)
	v_mfma_f32_16x16x32_bf16 v[100:103], v[96:99], v[24:27], v[56:59]
	s_waitcnt lgkmcnt(6)
	v_mfma_f32_16x16x32_bf16 v[96:99], v[176:179], v[24:27], v[60:63]
	s_waitcnt lgkmcnt(5)
	v_mfma_f32_16x16x32_bf16 v[88:91], v[180:183], v[24:27], v[64:67]
	s_waitcnt lgkmcnt(4)
	v_mfma_f32_16x16x32_bf16 v[80:83], v[184:187], v[24:27], v[68:71]
	s_waitcnt lgkmcnt(3)
	v_mfma_f32_16x16x32_bf16 v[68:71], v[236:239], v[24:27], v[76:79]
	s_waitcnt lgkmcnt(2)
	v_mfma_f32_16x16x32_bf16 v[64:67], v[240:243], v[24:27], v[172:175]
	s_waitcnt lgkmcnt(1)
	v_mfma_f32_16x16x32_bf16 v[60:63], v[248:251], v[24:27], v[224:227]
	s_waitcnt lgkmcnt(0)
	v_mfma_f32_16x16x32_bf16 v[56:59], v[192:195], v[24:27], v[212:215]
	s_branch .Lssd_A_join
.Lssd_A_1110:
	ds_read_b128 v[56:59], v118 offset:34816
	ds_read_b128 v[60:63], v118 offset:39168
	ds_read_b128 v[64:67], v118 offset:43520
	ds_read_b128 v[68:71], v118 offset:47872
	ds_read_b128 v[76:79], v147
	ds_read_b128 v[80:83], v118 offset:52224
	ds_read_b128 v[84:87], v118 offset:56576
	ds_read_b128 v[96:99], v147 offset:4352
	ds_read_b128 v[100:103], v147 offset:8704
	ds_read_b128 v[168:171], v147 offset:13056
	s_waitcnt lgkmcnt(9)
	v_mfma_f32_16x16x32_bf16 v[56:59], v[56:59], v[0:3], 0
	s_waitcnt lgkmcnt(8)
	v_mfma_f32_16x16x32_bf16 v[60:63], v[60:63], v[0:3], 0
	s_waitcnt lgkmcnt(7)
	v_mfma_f32_16x16x32_bf16 v[64:67], v[64:67], v[0:3], 0
	s_waitcnt lgkmcnt(6)
	v_mfma_f32_16x16x32_bf16 v[68:71], v[68:71], v[0:3], 0
	s_waitcnt lgkmcnt(5)
	v_mfma_f32_16x16x32_bf16 v[76:79], v[76:79], v[0:3], 0
	s_waitcnt lgkmcnt(2)
	v_mfma_f32_16x16x32_bf16 v[96:99], v[96:99], v[0:3], 0
	ds_read_b128 v[172:175], v118 offset:34880
	ds_read_b128 v[176:179], v118 offset:39232
	ds_read_b128 v[180:183], v118 offset:43584
	ds_read_b128 v[184:187], v118 offset:47936
	ds_read_b128 v[212:215], v147 offset:64
	ds_read_b128 v[216:219], v147 offset:4416
	v_mfma_f32_16x16x32_bf16 v[80:83], v[80:83], v[0:3], 0
	v_mfma_f32_16x16x32_bf16 v[84:87], v[84:87], v[0:3], 0
	s_waitcnt lgkmcnt(7)
	v_mfma_f32_16x16x32_bf16 v[100:103], v[100:103], v[0:3], 0
	s_waitcnt lgkmcnt(6)
	v_mfma_f32_16x16x32_bf16 v[72:75], v[168:171], v[0:3], 0
	ds_read_b128 v[168:171], v118 offset:52288
	ds_read_b128 v[220:223], v118 offset:56640
	ds_read_b128 v[232:235], v147 offset:8768
	ds_read_b128 v[236:239], v147 offset:13120
	s_waitcnt lgkmcnt(9)
	v_mfma_f32_16x16x32_bf16 v[56:59], v[172:175], v[8:11], v[56:59]
	s_waitcnt lgkmcnt(8)
	v_mfma_f32_16x16x32_bf16 v[60:63], v[176:179], v[8:11], v[60:63]
	s_waitcnt lgkmcnt(7)
	v_mfma_f32_16x16x32_bf16 v[64:67], v[180:183], v[8:11], v[64:67]
	s_waitcnt lgkmcnt(6)
	v_mfma_f32_16x16x32_bf16 v[68:71], v[184:187], v[8:11], v[68:71]
	s_waitcnt lgkmcnt(5)
	v_mfma_f32_16x16x32_bf16 v[76:79], v[212:215], v[8:11], v[76:79]
	s_waitcnt lgkmcnt(4)
	v_mfma_f32_16x16x32_bf16 v[96:99], v[216:219], v[8:11], v[96:99]
	ds_read_b128 v[172:175], v118 offset:34944
	ds_read_b128 v[176:179], v118 offset:39296
	ds_read_b128 v[180:183], v118 offset:43648
	ds_read_b128 v[184:187], v118 offset:48000
	ds_read_b128 v[216:219], v147 offset:128
	ds_read_b128 v[240:243], v147 offset:4480
	s_waitcnt lgkmcnt(9)
	v_mfma_f32_16x16x32_bf16 v[80:83], v[168:171], v[8:11], v[80:83]
	s_waitcnt lgkmcnt(8)
	v_mfma_f32_16x16x32_bf16 v[84:87], v[220:223], v[8:11], v[84:87]
	s_waitcnt lgkmcnt(7)
	v_mfma_f32_16x16x32_bf16 v[100:103], v[232:235], v[8:11], v[100:103]
	s_waitcnt lgkmcnt(6)
	v_mfma_f32_16x16x32_bf16 v[72:75], v[236:239], v[8:11], v[72:75]
	ds_read_b128 v[168:171], v118 offset:52352
	ds_read_b128 v[188:191], v118 offset:56704
	ds_read_b128 v[228:231], v147 offset:8832
	ds_read_b128 v[232:235], v147 offset:13184
	s_waitcnt lgkmcnt(9)
	v_mfma_f32_16x16x32_bf16 v[56:59], v[172:175], v[16:19], v[56:59]
	s_waitcnt lgkmcnt(8)
	v_mfma_f32_16x16x32_bf16 v[60:63], v[176:179], v[16:19], v[60:63]
	s_waitcnt lgkmcnt(7)
	v_mfma_f32_16x16x32_bf16 v[64:67], v[180:183], v[16:19], v[64:67]
	s_waitcnt lgkmcnt(6)
	v_mfma_f32_16x16x32_bf16 v[68:71], v[184:187], v[16:19], v[68:71]
	s_waitcnt lgkmcnt(5)
	v_mfma_f32_16x16x32_bf16 v[76:79], v[216:219], v[16:19], v[76:79]
	s_waitcnt lgkmcnt(4)
	v_mfma_f32_16x16x32_bf16 v[172:175], v[240:243], v[16:19], v[96:99]
	s_nop 2
	ds_read_b128 v[96:99], v118 offset:35008
	ds_read_b128 v[176:179], v118 offset:39360
	ds_read_b128 v[180:183], v118 offset:43712
	ds_read_b128 v[184:187], v118 offset:48064
	ds_read_b128 v[236:239], v147 offset:192
	ds_read_b128 v[240:243], v147 offset:4544
	s_waitcnt lgkmcnt(9)
	v_mfma_f32_16x16x32_bf16 v[168:171], v[168:171], v[16:19], v[80:83]
	s_waitcnt lgkmcnt(8)
	v_mfma_f32_16x16x32_bf16 v[84:87], v[188:191], v[16:19], v[84:87]
	s_waitcnt lgkmcnt(7)
	v_mfma_f32_16x16x32_bf16 v[224:227], v[228:231], v[16:19], v[100:103]
	s_waitcnt lgkmcnt(6)
	v_mfma_f32_16x16x32_bf16 v[212:215], v[232:235], v[16:19], v[72:75]
	s_nop 2
	ds_read_b128 v[72:75], v118 offset:52416
	ds_read_b128 v[228:231], v118 offset:56768
	ds_read_b128 v[248:251], v147 offset:8896
	ds_read_b128 v[192:195], v147 offset:13248
	s_waitcnt lgkmcnt(9)
	v_mfma_f32_16x16x32_bf16 v[100:103], v[96:99], v[24:27], v[56:59]
	s_waitcnt lgkmcnt(8)
	v_mfma_f32_16x16x32_bf16 v[96:99], v[176:179], v[24:27], v[60:63]
	s_waitcnt lgkmcnt(7)
	v_mfma_f32_16x16x32_bf16 v[88:91], v[180:183], v[24:27], v[64:67]
	s_waitcnt lgkmcnt(6)
	v_mfma_f32_16x16x32_bf16 v[80:83], v[184:187], v[24:27], v[68:71]
	s_waitcnt lgkmcnt(5)
	v_mfma_f32_16x16x32_bf16 v[68:71], v[236:239], v[24:27], v[76:79]
	s_waitcnt lgkmcnt(4)
	v_mfma_f32_16x16x32_bf16 v[64:67], v[240:243], v[24:27], v[172:175]
	s_waitcnt lgkmcnt(3)
	v_mfma_f32_16x16x32_bf16 v[92:95], v[72:75], v[24:27], v[168:171]
	s_waitcnt lgkmcnt(2)
	v_mfma_f32_16x16x32_bf16 v[84:87], v[228:231], v[24:27], v[84:87]
	s_waitcnt lgkmcnt(1)
	v_mfma_f32_16x16x32_bf16 v[60:63], v[248:251], v[24:27], v[224:227]
	s_waitcnt lgkmcnt(0)
	v_mfma_f32_16x16x32_bf16 v[56:59], v[192:195], v[24:27], v[212:215]
	s_branch .Lssd_A_join
; #define MFMA16(a, b, c) __builtin_amdgcn_mfma_f32_16x16x32_bf16((a), (b), (c), 0, 0, 0)
; __device__ __forceinline__ void phase_C1(const Args& a, unsigned char* ws, const int bid, int l, LAS unsigned char* lds, int tid, int wave, int lane) {
;     ...
;             {
;                 bf16x8 cqv[2], bq[2][4], hq[2][2];
;     ...
;                 SSD_LDH(0, 0);
; #pragma unroll
;                 for (int h2 = 0; h2 < 8; ++h2) { const int cb = h2 & 1, s_ = h2 >> 1, hf_ = h2 & 1;
;                     if (h2 < 7) SSD_LDH(cb ^ 1, h2 + 1);
;                     __builtin_amdgcn_sched_barrier(0);
; #pragma unroll
;                     for (int k = 0; k < 4; ++k) accA[4 * hf_ + k] = MFMA16(bq[cb][k], cqv[s_ & 1], accA[4 * hf_ + k]);
; #pragma unroll
;                     for (int p = 0; p < 2; ++p) accC[2 * hf_ + p] = MFMA16(hq[cb][p], cqv[s_ & 1], accC[2 * hf_ + p]);
;                     __builtin_amdgcn_sched_barrier(0); }
.Lssd_A_0111:
	ds_read_b128 v[64:67], v118 offset:43520
	ds_read_b128 v[68:71], v118 offset:47872
	ds_read_b128 v[76:79], v147
	ds_read_b128 v[80:83], v118 offset:52224
	ds_read_b128 v[84:87], v118 offset:56576
	ds_read_b128 v[88:91], v118 offset:60928
	ds_read_b128 v[92:95], v118 offset:65280
	ds_read_b128 v[96:99], v147 offset:4352
	ds_read_b128 v[100:103], v147 offset:8704
	ds_read_b128 v[168:171], v147 offset:13056
	s_waitcnt lgkmcnt(9)
	v_mfma_f32_16x16x32_bf16 v[64:67], v[64:67], v[0:3], 0
	s_waitcnt lgkmcnt(8)
	v_mfma_f32_16x16x32_bf16 v[68:71], v[68:71], v[0:3], 0
	s_waitcnt lgkmcnt(7)
	v_mfma_f32_16x16x32_bf16 v[76:79], v[76:79], v[0:3], 0
	s_waitcnt lgkmcnt(2)
	v_mfma_f32_16x16x32_bf16 v[96:99], v[96:99], v[0:3], 0
	ds_read_b128 v[180:183], v118 offset:43584
	ds_read_b128 v[184:187], v118 offset:47936
	ds_read_b128 v[212:215], v147 offset:64
	ds_read_b128 v[216:219], v147 offset:4416
	v_mfma_f32_16x16x32_bf16 v[80:83], v[80:83], v[0:3], 0
	v_mfma_f32_16x16x32_bf16 v[84:87], v[84:87], v[0:3], 0
	v_mfma_f32_16x16x32_bf16 v[88:91], v[88:91], v[0:3], 0
	v_mfma_f32_16x16x32_bf16 v[92:95], v[92:95], v[0:3], 0
	s_waitcnt lgkmcnt(5)
	v_mfma_f32_16x16x32_bf16 v[100:103], v[100:103], v[0:3], 0
	s_waitcnt lgkmcnt(4)
	v_mfma_f32_16x16x32_bf16 v[72:75], v[168:171], v[0:3], 0
	ds_read_b128 v[168:171], v118 offset:52288
	ds_read_b128 v[220:223], v118 offset:56640
	ds_read_b128 v[224:227], v118 offset:60992
	ds_read_b128 v[228:231], v118 offset:65344
	ds_read_b128 v[232:235], v147 offset:8768
	ds_read_b128 v[236:239], v147 offset:13120
	s_waitcnt lgkmcnt(9)
	v_mfma_f32_16x16x32_bf16 v[64:67], v[180:183], v[8:11], v[64:67]
	s_waitcnt lgkmcnt(8)
	v_mfma_f32_16x16x32_bf16 v[68:71], v[184:187], v[8:11], v[68:71]
	s_waitcnt lgkmcnt(7)
	v_mfma_f32_16x16x32_bf16 v[76:79], v[212:215], v[8:11], v[76:79]
	s_waitcnt lgkmcnt(6)
	v_mfma_f32_16x16x32_bf16 v[96:99], v[216:219], v[8:11], v[96:99]
	ds_read_b128 v[180:183], v118 offset:43648
	ds_read_b128 v[184:187], v118 offset:48000
	ds_read_b128 v[216:219], v147 offset:128
	ds_read_b128 v[240:243], v147 offset:4480
	s_waitcnt lgkmcnt(9)
	v_mfma_f32_16x16x32_bf16 v[80:83], v[168:171], v[8:11], v[80:83]
	s_waitcnt lgkmcnt(8)
	v_mfma_f32_16x16x32_bf16 v[84:87], v[220:223], v[8:11], v[84:87]
	s_waitcnt lgkmcnt(7)
	v_mfma_f32_16x16x32_bf16 v[88:91], v[224:227], v[8:11], v[88:91]
	s_waitcnt lgkmcnt(6)
	v_mfma_f32_16x16x32_bf16 v[92:95], v[228:231], v[8:11], v[92:95]
	s_waitcnt lgkmcnt(5)
	v_mfma_f32_16x16x32_bf16 v[100:103], v[232:235], v[8:11], v[100:103]
	s_waitcnt lgkmcnt(4)
	v_mfma_f32_16x16x32_bf16 v[72:75], v[236:239], v[8:11], v[72:75]
	ds_read_b128 v[168:171], v118 offset:52352
	ds_read_b128 v[188:191], v118 offset:56704
	ds_read_b128 v[220:223], v118 offset:61056
	ds_read_b128 v[224:227], v118 offset:65408
	ds_read_b128 v[228:231], v147 offset:8832
	ds_read_b128 v[232:235], v147 offset:13184
	s_waitcnt lgkmcnt(9)
	v_mfma_f32_16x16x32_bf16 v[64:67], v[180:183], v[16:19], v[64:67]
	s_waitcnt lgkmcnt(8)
	v_mfma_f32_16x16x32_bf16 v[68:71], v[184:187], v[16:19], v[68:71]
	s_waitcnt lgkmcnt(7)
	v_mfma_f32_16x16x32_bf16 v[76:79], v[216:219], v[16:19], v[76:79]
	s_waitcnt lgkmcnt(6)
	v_mfma_f32_16x16x32_bf16 v[172:175], v[240:243], v[16:19], v[96:99]
	s_nop 2
	ds_read_b128 v[180:183], v118 offset:43712
	ds_read_b128 v[184:187], v118 offset:48064
	ds_read_b128 v[236:239], v147 offset:192
	ds_read_b128 v[240:243], v147 offset:4544
	s_waitcnt lgkmcnt(9)
	v_mfma_f32_16x16x32_bf16 v[168:171], v[168:171], v[16:19], v[80:83]
	s_waitcnt lgkmcnt(8)
	v_mfma_f32_16x16x32_bf16 v[84:87], v[188:191], v[16:19], v[84:87]
	s_waitcnt lgkmcnt(7)
	v_mfma_f32_16x16x32_bf16 v[188:191], v[220:223], v[16:19], v[88:91]
	s_waitcnt lgkmcnt(6)
	v_mfma_f32_16x16x32_bf16 v[220:223], v[224:227], v[16:19], v[92:95]
	s_waitcnt lgkmcnt(5)
	v_mfma_f32_16x16x32_bf16 v[224:227], v[228:231], v[16:19], v[100:103]
	s_waitcnt lgkmcnt(4)
	v_mfma_f32_16x16x32_bf16 v[212:215], v[232:235], v[16:19], v[72:75]
	s_nop 2
	ds_read_b128 v[72:75], v118 offset:52416
	ds_read_b128 v[228:231], v118 offset:56768
	ds_read_b128 v[232:235], v118 offset:61120
	ds_read_b128 v[244:247], v118 offset:65472
	ds_read_b128 v[248:251], v147 offset:8896
	ds_read_b128 v[192:195], v147 offset:13248
	s_waitcnt lgkmcnt(9)
	v_mfma_f32_16x16x32_bf16 v[88:91], v[180:183], v[24:27], v[64:67]
	s_waitcnt lgkmcnt(8)
	v_mfma_f32_16x16x32_bf16 v[80:83], v[184:187], v[24:27], v[68:71]
	s_waitcnt lgkmcnt(7)
	v_mfma_f32_16x16x32_bf16 v[68:71], v[236:239], v[24:27], v[76:79]
	s_waitcnt lgkmcnt(6)
	v_mfma_f32_16x16x32_bf16 v[64:67], v[240:243], v[24:27], v[172:175]
	s_waitcnt lgkmcnt(5)
	v_mfma_f32_16x16x32_bf16 v[92:95], v[72:75], v[24:27], v[168:171]
	s_waitcnt lgkmcnt(4)
	v_mfma_f32_16x16x32_bf16 v[84:87], v[228:231], v[24:27], v[84:87]
	s_waitcnt lgkmcnt(3)
	v_mfma_f32_16x16x32_bf16 v[76:79], v[232:235], v[24:27], v[188:191]
	s_waitcnt lgkmcnt(2)
	v_mfma_f32_16x16x32_bf16 v[72:75], v[244:247], v[24:27], v[220:223]
	s_waitcnt lgkmcnt(1)
	v_mfma_f32_16x16x32_bf16 v[60:63], v[248:251], v[24:27], v[224:227]
	s_waitcnt lgkmcnt(0)
	v_mfma_f32_16x16x32_bf16 v[56:59], v[192:195], v[24:27], v[212:215]
	s_branch .Lssd_A_join
; #define MFMA16(a, b, c) __builtin_amdgcn_mfma_f32_16x16x32_bf16((a), (b), (c), 0, 0, 0)
; __device__ __forceinline__ void phase_C1(const Args& a, unsigned char* ws, const int bid, int l, LAS unsigned char* lds, int tid, int wave, int lane) {
;     ...
;             {
;                 bf16x8 cqv[2], bq[2][4], hq[2][2];
;     ...
;                 SSD_LDH(0, 0);
; #pragma unroll
;                 for (int h2 = 0; h2 < 8; ++h2) { const int cb = h2 & 1, s_ = h2 >> 1, hf_ = h2 & 1;
;                     if (h2 < 7) SSD_LDH(cb ^ 1, h2 + 1);
;                     __builtin_amdgcn_sched_barrier(0);
; #pragma unroll
;                     for (int k = 0; k < 4; ++k) accA[4 * hf_ + k] = MFMA16(bq[cb][k], cqv[s_ & 1], accA[4 * hf_ + k]);
; #pragma unroll
;                     for (int p = 0; p < 2; ++p) accC[2 * hf_ + p] = MFMA16(hq[cb][p], cqv[s_ & 1], accC[2 * hf_ + p]);
;                     __builtin_amdgcn_sched_barrier(0); }
.Lssd_A_0011:
	ds_read_b128 v[76:79], v147
	ds_read_b128 v[80:83], v118 offset:52224
	ds_read_b128 v[84:87], v118 offset:56576
	ds_read_b128 v[88:91], v118 offset:60928
	ds_read_b128 v[92:95], v118 offset:65280
	ds_read_b128 v[96:99], v147 offset:4352
	ds_read_b128 v[100:103], v147 offset:8704
	ds_read_b128 v[168:171], v147 offset:13056
	s_waitcnt lgkmcnt(7)
	v_mfma_f32_16x16x32_bf16 v[76:79], v[76:79], v[0:3], 0
	s_waitcnt lgkmcnt(2)
	v_mfma_f32_16x16x32_bf16 v[96:99], v[96:99], v[0:3], 0
	ds_read_b128 v[212:215], v147 offset:64
	ds_read_b128 v[216:219], v147 offset:4416
	v_mfma_f32_16x16x32_bf16 v[80:83], v[80:83], v[0:3], 0
	v_mfma_f32_16x16x32_bf16 v[84:87], v[84:87], v[0:3], 0
	v_mfma_f32_16x16x32_bf16 v[88:91], v[88:91], v[0:3], 0
	v_mfma_f32_16x16x32_bf16 v[92:95], v[92:95], v[0:3], 0
	s_waitcnt lgkmcnt(3)
	v_mfma_f32_16x16x32_bf16 v[100:103], v[100:103], v[0:3], 0
	s_waitcnt lgkmcnt(2)
	v_mfma_f32_16x16x32_bf16 v[72:75], v[168:171], v[0:3], 0
	ds_read_b128 v[168:171], v118 offset:52288
	ds_read_b128 v[220:223], v118 offset:56640
	ds_read_b128 v[224:227], v118 offset:60992
	ds_read_b128 v[228:231], v118 offset:65344
	ds_read_b128 v[232:235], v147 offset:8768
	ds_read_b128 v[236:239], v147 offset:13120
	s_waitcnt lgkmcnt(7)
	v_mfma_f32_16x16x32_bf16 v[76:79], v[212:215], v[8:11], v[76:79]
	s_waitcnt lgkmcnt(6)
	v_mfma_f32_16x16x32_bf16 v[96:99], v[216:219], v[8:11], v[96:99]
	ds_read_b128 v[216:219], v147 offset:128
	ds_read_b128 v[240:243], v147 offset:4480
	s_waitcnt lgkmcnt(7)
	v_mfma_f32_16x16x32_bf16 v[80:83], v[168:171], v[8:11], v[80:83]
	s_waitcnt lgkmcnt(6)
	v_mfma_f32_16x16x32_bf16 v[84:87], v[220:223], v[8:11], v[84:87]
	s_waitcnt lgkmcnt(5)
	v_mfma_f32_16x16x32_bf16 v[88:91], v[224:227], v[8:11], v[88:91]
	s_waitcnt lgkmcnt(4)
	v_mfma_f32_16x16x32_bf16 v[92:95], v[228:231], v[8:11], v[92:95]
	s_waitcnt lgkmcnt(3)
	v_mfma_f32_16x16x32_bf16 v[100:103], v[232:235], v[8:11], v[100:103]
	s_waitcnt lgkmcnt(2)
	v_mfma_f32_16x16x32_bf16 v[72:75], v[236:239], v[8:11], v[72:75]
	ds_read_b128 v[168:171], v118 offset:52352
	ds_read_b128 v[188:191], v118 offset:56704
	ds_read_b128 v[220:223], v118 offset:61056
	ds_read_b128 v[224:227], v118 offset:65408
	ds_read_b128 v[228:231], v147 offset:8832
	ds_read_b128 v[232:235], v147 offset:13184
	s_waitcnt lgkmcnt(7)
	v_mfma_f32_16x16x32_bf16 v[76:79], v[216:219], v[16:19], v[76:79]
	s_waitcnt lgkmcnt(6)
	v_mfma_f32_16x16x32_bf16 v[172:175], v[240:243], v[16:19], v[96:99]
	s_nop 2
	ds_read_b128 v[236:239], v147 offset:192
	ds_read_b128 v[240:243], v147 offset:4544
	s_waitcnt lgkmcnt(7)
	v_mfma_f32_16x16x32_bf16 v[168:171], v[168:171], v[16:19], v[80:83]
	s_waitcnt lgkmcnt(6)
	v_mfma_f32_16x16x32_bf16 v[84:87], v[188:191], v[16:19], v[84:87]
	s_waitcnt lgkmcnt(5)
	v_mfma_f32_16x16x32_bf16 v[188:191], v[220:223], v[16:19], v[88:91]
	s_waitcnt lgkmcnt(4)
	v_mfma_f32_16x16x32_bf16 v[220:223], v[224:227], v[16:19], v[92:95]
	s_waitcnt lgkmcnt(3)
	v_mfma_f32_16x16x32_bf16 v[224:227], v[228:231], v[16:19], v[100:103]
	s_waitcnt lgkmcnt(2)
	v_mfma_f32_16x16x32_bf16 v[212:215], v[232:235], v[16:19], v[72:75]
	s_nop 2
	ds_read_b128 v[72:75], v118 offset:52416
	ds_read_b128 v[228:231], v118 offset:56768
	ds_read_b128 v[232:235], v118 offset:61120
	ds_read_b128 v[244:247], v118 offset:65472
	ds_read_b128 v[248:251], v147 offset:8896
	ds_read_b128 v[192:195], v147 offset:13248
	s_waitcnt lgkmcnt(7)
	v_mfma_f32_16x16x32_bf16 v[68:71], v[236:239], v[24:27], v[76:79]
	s_waitcnt lgkmcnt(6)
	v_mfma_f32_16x16x32_bf16 v[64:67], v[240:243], v[24:27], v[172:175]
	s_waitcnt lgkmcnt(5)
	v_mfma_f32_16x16x32_bf16 v[92:95], v[72:75], v[24:27], v[168:171]
	s_waitcnt lgkmcnt(4)
	v_mfma_f32_16x16x32_bf16 v[84:87], v[228:231], v[24:27], v[84:87]
	s_waitcnt lgkmcnt(3)
	v_mfma_f32_16x16x32_bf16 v[76:79], v[232:235], v[24:27], v[188:191]
	s_waitcnt lgkmcnt(2)
	v_mfma_f32_16x16x32_bf16 v[72:75], v[244:247], v[24:27], v[220:223]
	s_waitcnt lgkmcnt(1)
	v_mfma_f32_16x16x32_bf16 v[60:63], v[248:251], v[24:27], v[224:227]
	s_waitcnt lgkmcnt(0)
	v_mfma_f32_16x16x32_bf16 v[56:59], v[192:195], v[24:27], v[212:215]
	s_branch .Lssd_A_join
; #define MFMA16(a, b, c) __builtin_amdgcn_mfma_f32_16x16x32_bf16((a), (b), (c), 0, 0, 0)
; __device__ __forceinline__ void phase_C1(const Args& a, unsigned char* ws, const int bid, int l, LAS unsigned char* lds, int tid, int wave, int lane) {
;     ...
;             {
;                 bf16x8 cqv[2], bq[2][4], hq[2][2];
;     ...
;                 SSD_LDH(0, 0);
; #pragma unroll
;                 for (int h2 = 0; h2 < 8; ++h2) { const int cb = h2 & 1, s_ = h2 >> 1, hf_ = h2 & 1;
;                     if (h2 < 7) SSD_LDH(cb ^ 1, h2 + 1);
;                     __builtin_amdgcn_sched_barrier(0);
; #pragma unroll
;                     for (int k = 0; k < 4; ++k) accA[4 * hf_ + k] = MFMA16(bq[cb][k], cqv[s_ & 1], accA[4 * hf_ + k]);
; #pragma unroll
;                     for (int p = 0; p < 2; ++p) accC[2 * hf_ + p] = MFMA16(hq[cb][p], cqv[s_ & 1], accC[2 * hf_ + p]);
;                     __builtin_amdgcn_sched_barrier(0); }
.Lssd_A_0001:
	ds_read_b128 v[76:79], v147
	ds_read_b128 v[88:91], v118 offset:60928
	ds_read_b128 v[92:95], v118 offset:65280
	ds_read_b128 v[96:99], v147 offset:4352
	ds_read_b128 v[100:103], v147 offset:8704
	ds_read_b128 v[168:171], v147 offset:13056
	s_waitcnt lgkmcnt(5)
	v_mfma_f32_16x16x32_bf16 v[76:79], v[76:79], v[0:3], 0
	s_waitcnt lgkmcnt(2)
	v_mfma_f32_16x16x32_bf16 v[96:99], v[96:99], v[0:3], 0
	ds_read_b128 v[212:215], v147 offset:64
	ds_read_b128 v[216:219], v147 offset:4416
	v_mfma_f32_16x16x32_bf16 v[88:91], v[88:91], v[0:3], 0
	v_mfma_f32_16x16x32_bf16 v[92:95], v[92:95], v[0:3], 0
	s_waitcnt lgkmcnt(3)
	v_mfma_f32_16x16x32_bf16 v[100:103], v[100:103], v[0:3], 0
	s_waitcnt lgkmcnt(2)
	v_mfma_f32_16x16x32_bf16 v[72:75], v[168:171], v[0:3], 0
	ds_read_b128 v[224:227], v118 offset:60992
	ds_read_b128 v[228:231], v118 offset:65344
	ds_read_b128 v[232:235], v147 offset:8768
	ds_read_b128 v[236:239], v147 offset:13120
	s_waitcnt lgkmcnt(5)
	v_mfma_f32_16x16x32_bf16 v[76:79], v[212:215], v[8:11], v[76:79]
	s_waitcnt lgkmcnt(4)
	v_mfma_f32_16x16x32_bf16 v[96:99], v[216:219], v[8:11], v[96:99]
	ds_read_b128 v[216:219], v147 offset:128
	ds_read_b128 v[240:243], v147 offset:4480
	s_waitcnt lgkmcnt(5)
	v_mfma_f32_16x16x32_bf16 v[88:91], v[224:227], v[8:11], v[88:91]
	s_waitcnt lgkmcnt(4)
	v_mfma_f32_16x16x32_bf16 v[92:95], v[228:231], v[8:11], v[92:95]
	s_waitcnt lgkmcnt(3)
	v_mfma_f32_16x16x32_bf16 v[100:103], v[232:235], v[8:11], v[100:103]
	s_waitcnt lgkmcnt(2)
	v_mfma_f32_16x16x32_bf16 v[72:75], v[236:239], v[8:11], v[72:75]
	ds_read_b128 v[220:223], v118 offset:61056
	ds_read_b128 v[224:227], v118 offset:65408
	ds_read_b128 v[228:231], v147 offset:8832
	ds_read_b128 v[232:235], v147 offset:13184
	s_waitcnt lgkmcnt(5)
	v_mfma_f32_16x16x32_bf16 v[76:79], v[216:219], v[16:19], v[76:79]
	s_waitcnt lgkmcnt(4)
	v_mfma_f32_16x16x32_bf16 v[172:175], v[240:243], v[16:19], v[96:99]
	s_nop 2
	ds_read_b128 v[236:239], v147 offset:192
	ds_read_b128 v[240:243], v147 offset:4544
	s_waitcnt lgkmcnt(5)
	v_mfma_f32_16x16x32_bf16 v[188:191], v[220:223], v[16:19], v[88:91]
	s_waitcnt lgkmcnt(4)
	v_mfma_f32_16x16x32_bf16 v[220:223], v[224:227], v[16:19], v[92:95]
	s_waitcnt lgkmcnt(3)
	v_mfma_f32_16x16x32_bf16 v[224:227], v[228:231], v[16:19], v[100:103]
	s_waitcnt lgkmcnt(2)
	v_mfma_f32_16x16x32_bf16 v[212:215], v[232:235], v[16:19], v[72:75]
	s_nop 2
	ds_read_b128 v[232:235], v118 offset:61120
	ds_read_b128 v[244:247], v118 offset:65472
	ds_read_b128 v[248:251], v147 offset:8896
	ds_read_b128 v[192:195], v147 offset:13248
	s_waitcnt lgkmcnt(5)
	v_mfma_f32_16x16x32_bf16 v[68:71], v[236:239], v[24:27], v[76:79]
	s_waitcnt lgkmcnt(4)
	v_mfma_f32_16x16x32_bf16 v[64:67], v[240:243], v[24:27], v[172:175]
	s_waitcnt lgkmcnt(3)
	v_mfma_f32_16x16x32_bf16 v[76:79], v[232:235], v[24:27], v[188:191]
	s_waitcnt lgkmcnt(2)
	v_mfma_f32_16x16x32_bf16 v[72:75], v[244:247], v[24:27], v[220:223]
	s_waitcnt lgkmcnt(1)
	v_mfma_f32_16x16x32_bf16 v[60:63], v[248:251], v[24:27], v[224:227]
	s_waitcnt lgkmcnt(0)
	v_mfma_f32_16x16x32_bf16 v[56:59], v[192:195], v[24:27], v[212:215]
	s_branch .Lssd_A_join
.Lssd_A_join:
	s_cmp_eq_u32 s4, 7
	s_cbranch_scc1 .Lssd_A_join2
	s_add_i32 s74, s5, s72
	s_add_i32 s74, s74, 7
	s_add_i32 s75, s5, s4
	s_cmpk_eq_i32 s4, 0x48
	s_cselect_b32 s76, s3, s74
	s_cselect_b32 s77, s94, s75
	s_and_b64 s[74:75], s[42:43], exec
	s_cselect_b32 s74, s76, s77
	s_lshl_b32 s90, s74, 7
	s_ashr_i32 s91, s90, 31
	s_lshl_b64 s[74:75], s[90:91], 13
	s_add_u32 s76, s68, s74
	s_addc_u32 s77, s93, s75
	s_add_u32 s74, s76, s95
	s_addc_u32 s75, s77, 0
	s_add_u32 s74, s74, 0x1800
	s_addc_u32 s75, s75, 0
	v_readfirstlane_b32 vcc_lo, v164
	v_and_b32_e32 v168, 15, v164
	v_bfe_u32 v169, v164, 4, 2
	v_lshlrev_b32_e32 v168, 13, v168
	s_lshr_b32 vcc_lo, vcc_lo, 6
	s_sub_i32 vcc_hi, 11, vcc_lo
	s_cmp_lt_u32 vcc_lo, 4
	s_cselect_b32 vcc_lo, vcc_lo, vcc_hi
	s_lshl_b32 vcc_lo, vcc_lo, 17
	v_lshl_add_u32 v168, v169, 4, v168
	v_add_u32_e32 v168, vcc_lo, v168
	v_mov_b32_e32 v169, 0
	v_lshl_add_u64 v[168:169], s[74:75], 0, v[168:169]
	global_load_dwordx4 v[0:3], v[168:169], off
	global_load_dwordx4 v[8:11], v[168:169], off offset:64
	global_load_dwordx4 v[16:19], v[168:169], off offset:128
	global_load_dwordx4 v[24:27], v[168:169], off offset:192
